# GEMM-unit-start-zero-accumulators-once-instead-of-twice
# speedup vs baseline: 1.0132x; 1.0013x over previous
;     __device__ __forceinline__ bool next(int i, Unit& u) const { return (i < na) ? a.next(i, u) : b.next(i - na, u); }
; template <class Epi, bool ALIGN_EPI = true, bool SP2 = true, bool QUARTER = false, class Sched = Order>
; __device__ __forceinline__ void gemm_phase(PG8_LAS unsigned char* lds, const Gemm g, const Sched& S, const Epi& E) {
;     ...
;     for (;;) {
;         const bool has_next = S.next(ui + 1, nxt);
;         const char* nA = has_next ? (const char*)(g.A + (size_t)nxt.z * g.zA) + (size_t)nxt.pm * tstepA : cA; const char* nB = has_next ? (const char*)(g.Bt + (size_t)nxt.z * g.zB) + (size_t)nxt.pn * tstepB : cB;
;         for (int t = 0; t < nt; t += 2) {
;             const bool last = (t == nt - 2);
;             const char* a1 = cA + (size_t)(t + 1) * kstep;
;             const char* a2 = last ? nA : cA + (size_t)(t + 2) * kstep; const char* b2 = last ? nB : cB + (size_t)(t + 2) * kstep;
;             const char* a3 = a2 + kstep; const char* b3 = b2 + kstep;
;     ...
; #pragma unroll
;         for (int a = 0; a < 2; ++a)
; #pragma unroll
;             for (int b = 0; b < 2; ++b)
; #pragma unroll
;                 for (int m = 0; m < 4; ++m)
; #pragma unroll
;                     for (int n = 0; n < 2; ++n) acc[a][b][m][n] = (f32x4){0.f, 0.f, 0.f, 0.f};
.LBB0_156:
	s_ashr_i32 s97, s96, 31
	s_lshl_b64 s[0:1], s[96:97], 19
	s_add_u32 s84, s76, s0
	s_addc_u32 s85, s77, s1
	s_ashr_i32 s95, s94, 31
	s_lshl_b64 s[0:1], s[94:95], 19
	v_readlane_b32 s16, v255, 19
	s_add_u32 s0, s78, s0
	v_readlane_b32 s17, v255, 20
	s_addc_u32 s1, s79, s1
	s_andn2_b64 vcc, exec, s[16:17]
	s_cbranch_vccz .Lmy_zr_0
	v_mov_b32_e32 v125, 0
	v_mov_b32_e32 v124, v125
	v_mov_b32_e32 v123, v125
	v_mov_b32_e32 v122, v125
	v_mov_b32_e32 v129, v125
	v_mov_b32_e32 v128, v125
	v_mov_b32_e32 v127, v125
	v_mov_b32_e32 v126, v125
	v_mov_b32_e32 v113, v125
	v_mov_b32_e32 v112, v125
	v_mov_b32_e32 v111, v125
	v_mov_b32_e32 v110, v125
	v_mov_b32_e32 v109, v125
	v_mov_b32_e32 v108, v125
	v_mov_b32_e32 v107, v125
	v_mov_b32_e32 v106, v125
	v_mov_b32_e32 v97, v125
	v_mov_b32_e32 v96, v125
	v_mov_b32_e32 v95, v125
	v_mov_b32_e32 v94, v125
	v_mov_b32_e32 v93, v125
	v_mov_b32_e32 v92, v125
	v_mov_b32_e32 v91, v125
	v_mov_b32_e32 v90, v125
	v_mov_b32_e32 v81, v125
	v_mov_b32_e32 v80, v125
	v_mov_b32_e32 v79, v125
	v_mov_b32_e32 v78, v125
	v_mov_b32_e32 v77, v125
	v_mov_b32_e32 v76, v125
	v_mov_b32_e32 v75, v125
	v_mov_b32_e32 v74, v125
	v_mov_b32_e32 v121, v125
	v_mov_b32_e32 v120, v125
	v_mov_b32_e32 v119, v125
	v_mov_b32_e32 v118, v125
	v_mov_b32_e32 v117, v125
	v_mov_b32_e32 v116, v125
	v_mov_b32_e32 v115, v125
	v_mov_b32_e32 v114, v125
	v_mov_b32_e32 v105, v125
	v_mov_b32_e32 v104, v125
	v_mov_b32_e32 v103, v125
	v_mov_b32_e32 v102, v125
	v_mov_b32_e32 v101, v125
	v_mov_b32_e32 v100, v125
	v_mov_b32_e32 v99, v125
	v_mov_b32_e32 v98, v125
	v_mov_b32_e32 v89, v125
	v_mov_b32_e32 v88, v125
	v_mov_b32_e32 v87, v125
	v_mov_b32_e32 v86, v125
	v_mov_b32_e32 v85, v125
	v_mov_b32_e32 v84, v125
	v_mov_b32_e32 v83, v125
	v_mov_b32_e32 v82, v125
	v_mov_b32_e32 v73, v125
	v_mov_b32_e32 v72, v125
	v_mov_b32_e32 v71, v125
	v_mov_b32_e32 v70, v125
	v_mov_b32_e32 v69, v125
	v_mov_b32_e32 v68, v125
	v_mov_b32_e32 v67, v125
	v_mov_b32_e32 v66, v125
	v_mov_b32_e32 v65, v125
	v_mov_b32_e32 v64, v125
	v_mov_b32_e32 v63, v125
	v_mov_b32_e32 v62, v125
	v_mov_b32_e32 v61, v125
	v_mov_b32_e32 v60, v125
	v_mov_b32_e32 v59, v125
	v_mov_b32_e32 v58, v125
	v_mov_b32_e32 v49, v125
	v_mov_b32_e32 v48, v125
	v_mov_b32_e32 v47, v125
	v_mov_b32_e32 v46, v125
	v_mov_b32_e32 v45, v125
	v_mov_b32_e32 v44, v125
	v_mov_b32_e32 v43, v125
	v_mov_b32_e32 v42, v125
	v_mov_b32_e32 v33, v125
	v_mov_b32_e32 v32, v125
	v_mov_b32_e32 v31, v125
	v_mov_b32_e32 v30, v125
	v_mov_b32_e32 v29, v125
	v_mov_b32_e32 v28, v125
	v_mov_b32_e32 v27, v125
	v_mov_b32_e32 v26, v125
	v_mov_b32_e32 v17, v125
	v_mov_b32_e32 v16, v125
	v_mov_b32_e32 v15, v125
	v_mov_b32_e32 v14, v125
	v_mov_b32_e32 v13, v125
	v_mov_b32_e32 v12, v125
	v_mov_b32_e32 v11, v125
	v_mov_b32_e32 v10, v125
	v_mov_b32_e32 v57, v125
	v_mov_b32_e32 v56, v125
	v_mov_b32_e32 v55, v125
	v_mov_b32_e32 v54, v125
	v_mov_b32_e32 v53, v125
	v_mov_b32_e32 v52, v125
	v_mov_b32_e32 v51, v125
	v_mov_b32_e32 v50, v125
	v_mov_b32_e32 v41, v125
	v_mov_b32_e32 v40, v125
	v_mov_b32_e32 v39, v125
	v_mov_b32_e32 v38, v125
	v_mov_b32_e32 v37, v125
	v_mov_b32_e32 v36, v125
	v_mov_b32_e32 v35, v125
	v_mov_b32_e32 v34, v125
	v_mov_b32_e32 v25, v125
	v_mov_b32_e32 v24, v125
	v_mov_b32_e32 v23, v125
	v_mov_b32_e32 v22, v125
	v_mov_b32_e32 v21, v125
	v_mov_b32_e32 v20, v125
	v_mov_b32_e32 v19, v125
	v_mov_b32_e32 v18, v125
	v_mov_b32_e32 v9, v125
	v_mov_b32_e32 v8, v125
	v_mov_b32_e32 v7, v125
	v_mov_b32_e32 v6, v125
	v_mov_b32_e32 v5, v125
	v_mov_b32_e32 v4, v125
	v_mov_b32_e32 v3, v125
	v_mov_b32_e32 v2, v125
	s_branch .LBB0_160
.Lmy_zr_0:
	s_and_b64 s[16:17], s[4:5], exec
	s_mov_b32 s36, s22
	s_cselect_b32 s7, s85, s13
	s_cselect_b32 s9, s84, s12
	s_cselect_b32 s22, s1, s11
	s_cselect_b32 s24, s0, s10
	s_add_u32 s25, s10, 0x100
	s_addc_u32 s26, s11, 0
	s_add_u32 s10, s12, 0x40080
	v_mov_b32_e32 v2, 0
	s_addc_u32 s11, s13, 0
	s_mov_b32 s12, 0
	v_mov_b32_e32 v3, v2
	v_mov_b32_e32 v4, v2
	v_mov_b32_e32 v5, v2
	v_mov_b32_e32 v6, v2
	v_mov_b32_e32 v7, v2
	v_mov_b32_e32 v8, v2
	v_mov_b32_e32 v9, v2
	v_mov_b32_e32 v18, v2
	v_mov_b32_e32 v19, v2
	v_mov_b32_e32 v20, v2
	v_mov_b32_e32 v21, v2
	v_mov_b32_e32 v22, v2
	v_mov_b32_e32 v23, v2
	v_mov_b32_e32 v24, v2
	v_mov_b32_e32 v25, v2
	v_mov_b32_e32 v34, v2
	v_mov_b32_e32 v35, v2
	v_mov_b32_e32 v36, v2
	v_mov_b32_e32 v37, v2
	v_mov_b32_e32 v38, v2
	v_mov_b32_e32 v39, v2
	v_mov_b32_e32 v40, v2
	v_mov_b32_e32 v41, v2
	v_mov_b32_e32 v50, v2
	v_mov_b32_e32 v51, v2
	v_mov_b32_e32 v52, v2
	v_mov_b32_e32 v53, v2
	v_mov_b32_e32 v54, v2
	v_mov_b32_e32 v55, v2
	v_mov_b32_e32 v56, v2
	v_mov_b32_e32 v57, v2
	v_mov_b32_e32 v10, v2
	v_mov_b32_e32 v11, v2
	v_mov_b32_e32 v12, v2
	v_mov_b32_e32 v13, v2
	v_mov_b32_e32 v14, v2
	v_mov_b32_e32 v15, v2
	v_mov_b32_e32 v16, v2
	v_mov_b32_e32 v17, v2
	v_mov_b32_e32 v26, v2
	v_mov_b32_e32 v27, v2
	v_mov_b32_e32 v28, v2
	v_mov_b32_e32 v29, v2
	v_mov_b32_e32 v30, v2
	v_mov_b32_e32 v31, v2
	v_mov_b32_e32 v32, v2
	v_mov_b32_e32 v33, v2
	v_mov_b32_e32 v42, v2
	v_mov_b32_e32 v43, v2
	v_mov_b32_e32 v44, v2
	v_mov_b32_e32 v45, v2
	v_mov_b32_e32 v46, v2
	v_mov_b32_e32 v47, v2
	v_mov_b32_e32 v48, v2
	v_mov_b32_e32 v49, v2
	v_mov_b32_e32 v58, v2
	v_mov_b32_e32 v59, v2
	v_mov_b32_e32 v60, v2
	v_mov_b32_e32 v61, v2
	v_mov_b32_e32 v62, v2
	v_mov_b32_e32 v63, v2
	v_mov_b32_e32 v64, v2
	v_mov_b32_e32 v65, v2
	v_mov_b32_e32 v66, v2
	v_mov_b32_e32 v67, v2
	v_mov_b32_e32 v68, v2
	v_mov_b32_e32 v69, v2
	v_mov_b32_e32 v70, v2
	v_mov_b32_e32 v71, v2
	v_mov_b32_e32 v72, v2
	v_mov_b32_e32 v73, v2
	v_mov_b32_e32 v82, v2
	v_mov_b32_e32 v83, v2
	v_mov_b32_e32 v84, v2
	v_mov_b32_e32 v85, v2
	v_mov_b32_e32 v86, v2
	v_mov_b32_e32 v87, v2
	v_mov_b32_e32 v88, v2
	v_mov_b32_e32 v89, v2
	v_mov_b32_e32 v98, v2
	v_mov_b32_e32 v99, v2
	v_mov_b32_e32 v100, v2
	v_mov_b32_e32 v101, v2
	v_mov_b32_e32 v102, v2
	v_mov_b32_e32 v103, v2
	v_mov_b32_e32 v104, v2
	v_mov_b32_e32 v105, v2
	v_mov_b32_e32 v114, v2
	v_mov_b32_e32 v115, v2
	v_mov_b32_e32 v116, v2
	v_mov_b32_e32 v117, v2
	v_mov_b32_e32 v118, v2
	v_mov_b32_e32 v119, v2
	v_mov_b32_e32 v120, v2
	v_mov_b32_e32 v121, v2
	v_mov_b32_e32 v74, v2
	v_mov_b32_e32 v75, v2
	v_mov_b32_e32 v76, v2
	v_mov_b32_e32 v77, v2
	v_mov_b32_e32 v78, v2
	v_mov_b32_e32 v79, v2
	v_mov_b32_e32 v80, v2
	v_mov_b32_e32 v81, v2
	v_mov_b32_e32 v90, v2
	v_mov_b32_e32 v91, v2
	v_mov_b32_e32 v92, v2
	v_mov_b32_e32 v93, v2
	v_mov_b32_e32 v94, v2
	v_mov_b32_e32 v95, v2
	v_mov_b32_e32 v96, v2
	v_mov_b32_e32 v97, v2
	v_mov_b32_e32 v106, v2
	v_mov_b32_e32 v107, v2
	v_mov_b32_e32 v108, v2
	v_mov_b32_e32 v109, v2
	v_mov_b32_e32 v110, v2
	v_mov_b32_e32 v111, v2
	v_mov_b32_e32 v112, v2
	v_mov_b32_e32 v113, v2
	v_mov_b32_e32 v126, v2
	v_mov_b32_e32 v127, v2
	v_mov_b32_e32 v128, v2
	v_mov_b32_e32 v129, v2
	v_mov_b32_e32 v122, v2
	v_mov_b32_e32 v123, v2
	v_mov_b32_e32 v124, v2
	v_mov_b32_e32 v125, v2

;     __device__ __forceinline__ bool next(int i, Unit& u) const { return (i < na) ? a.next(i, u) : b.next(i - na, u); }
; template <class Epi, bool ALIGN_EPI = true, bool SP2 = true, bool QUARTER = false, class Sched = Order>
; __device__ __forceinline__ void gemm_phase(PG8_LAS unsigned char* lds, const Gemm g, const Sched& S, const Epi& E) {
;     ...
;     for (;;) {
;         const bool has_next = S.next(ui + 1, nxt);
;         const char* nA = has_next ? (const char*)(g.A + (size_t)nxt.z * g.zA) + (size_t)nxt.pm * tstepA : cA; const char* nB = has_next ? (const char*)(g.Bt + (size_t)nxt.z * g.zB) + (size_t)nxt.pn * tstepB : cB;
;         for (int t = 0; t < nt; t += 2) {
;             const bool last = (t == nt - 2);
;             const char* a1 = cA + (size_t)(t + 1) * kstep;
;             const char* a2 = last ? nA : cA + (size_t)(t + 2) * kstep; const char* b2 = last ? nB : cB + (size_t)(t + 2) * kstep;
;             const char* a3 = a2 + kstep; const char* b3 = b2 + kstep;
;     ...
; #pragma unroll
;         for (int a = 0; a < 2; ++a)
; #pragma unroll
;             for (int b = 0; b < 2; ++b)
; #pragma unroll
;                 for (int m = 0; m < 4; ++m)
; #pragma unroll
;                     for (int n = 0; n < 2; ++n) acc[a][b][m][n] = (f32x4){0.f, 0.f, 0.f, 0.f};
.LBB0_794:
	s_andn2_b64 vcc, exec, s[8:9]
	s_cbranch_vccz .Lmy_zr_1
	v_mov_b32_e32 v125, 0
	v_mov_b32_e32 v124, v125
	v_mov_b32_e32 v123, v125
	v_mov_b32_e32 v122, v125
	v_mov_b32_e32 v129, v125
	v_mov_b32_e32 v128, v125
	v_mov_b32_e32 v127, v125
	v_mov_b32_e32 v126, v125
	v_mov_b32_e32 v113, v125
	v_mov_b32_e32 v112, v125
	v_mov_b32_e32 v111, v125
	v_mov_b32_e32 v110, v125
	v_mov_b32_e32 v109, v125
	v_mov_b32_e32 v108, v125
	v_mov_b32_e32 v107, v125
	v_mov_b32_e32 v106, v125
	v_mov_b32_e32 v97, v125
	v_mov_b32_e32 v96, v125
	v_mov_b32_e32 v95, v125
	v_mov_b32_e32 v94, v125
	v_mov_b32_e32 v93, v125
	v_mov_b32_e32 v92, v125
	v_mov_b32_e32 v91, v125
	v_mov_b32_e32 v90, v125
	v_mov_b32_e32 v81, v125
	v_mov_b32_e32 v80, v125
	v_mov_b32_e32 v79, v125
	v_mov_b32_e32 v78, v125
	v_mov_b32_e32 v77, v125
	v_mov_b32_e32 v76, v125
	v_mov_b32_e32 v75, v125
	v_mov_b32_e32 v74, v125
	v_mov_b32_e32 v121, v125
	v_mov_b32_e32 v120, v125
	v_mov_b32_e32 v119, v125
	v_mov_b32_e32 v118, v125
	v_mov_b32_e32 v117, v125
	v_mov_b32_e32 v116, v125
	v_mov_b32_e32 v115, v125
	v_mov_b32_e32 v114, v125
	v_mov_b32_e32 v105, v125
	v_mov_b32_e32 v104, v125
	v_mov_b32_e32 v103, v125
	v_mov_b32_e32 v102, v125
	v_mov_b32_e32 v101, v125
	v_mov_b32_e32 v100, v125
	v_mov_b32_e32 v99, v125
	v_mov_b32_e32 v98, v125
	v_mov_b32_e32 v89, v125
	v_mov_b32_e32 v88, v125
	v_mov_b32_e32 v87, v125
	v_mov_b32_e32 v86, v125
	v_mov_b32_e32 v85, v125
	v_mov_b32_e32 v84, v125
	v_mov_b32_e32 v83, v125
	v_mov_b32_e32 v82, v125
	v_mov_b32_e32 v73, v125
	v_mov_b32_e32 v72, v125
	v_mov_b32_e32 v71, v125
	v_mov_b32_e32 v70, v125
	v_mov_b32_e32 v69, v125
	v_mov_b32_e32 v68, v125
	v_mov_b32_e32 v67, v125
	v_mov_b32_e32 v66, v125
	v_mov_b32_e32 v65, v125
	v_mov_b32_e32 v64, v125
	v_mov_b32_e32 v63, v125
	v_mov_b32_e32 v62, v125
	v_mov_b32_e32 v61, v125
	v_mov_b32_e32 v60, v125
	v_mov_b32_e32 v59, v125
	v_mov_b32_e32 v58, v125
	v_mov_b32_e32 v49, v125
	v_mov_b32_e32 v48, v125
	v_mov_b32_e32 v47, v125
	v_mov_b32_e32 v46, v125
	v_mov_b32_e32 v45, v125
	v_mov_b32_e32 v44, v125
	v_mov_b32_e32 v43, v125
	v_mov_b32_e32 v42, v125
	v_mov_b32_e32 v33, v125
	v_mov_b32_e32 v32, v125
	v_mov_b32_e32 v31, v125
	v_mov_b32_e32 v30, v125
	v_mov_b32_e32 v29, v125
	v_mov_b32_e32 v28, v125
	v_mov_b32_e32 v27, v125
	v_mov_b32_e32 v26, v125
	v_mov_b32_e32 v17, v125
	v_mov_b32_e32 v16, v125
	v_mov_b32_e32 v15, v125
	v_mov_b32_e32 v14, v125
	v_mov_b32_e32 v13, v125
	v_mov_b32_e32 v12, v125
	v_mov_b32_e32 v11, v125
	v_mov_b32_e32 v10, v125
	v_mov_b32_e32 v57, v125
	v_mov_b32_e32 v56, v125
	v_mov_b32_e32 v55, v125
	v_mov_b32_e32 v54, v125
	v_mov_b32_e32 v53, v125
	v_mov_b32_e32 v52, v125
	v_mov_b32_e32 v51, v125
	v_mov_b32_e32 v50, v125
	v_mov_b32_e32 v41, v125
	v_mov_b32_e32 v40, v125
	v_mov_b32_e32 v39, v125
	v_mov_b32_e32 v38, v125
	v_mov_b32_e32 v37, v125
	v_mov_b32_e32 v36, v125
	v_mov_b32_e32 v35, v125
	v_mov_b32_e32 v34, v125
	v_mov_b32_e32 v25, v125
	v_mov_b32_e32 v24, v125
	v_mov_b32_e32 v23, v125
	v_mov_b32_e32 v22, v125
	v_mov_b32_e32 v21, v125
	v_mov_b32_e32 v20, v125
	v_mov_b32_e32 v19, v125
	v_mov_b32_e32 v18, v125
	v_mov_b32_e32 v9, v125
	v_mov_b32_e32 v8, v125
	v_mov_b32_e32 v7, v125
	v_mov_b32_e32 v6, v125
	v_mov_b32_e32 v5, v125
	v_mov_b32_e32 v4, v125
	v_mov_b32_e32 v3, v125
	v_mov_b32_e32 v2, v125
	s_branch .LBB0_797
.Lmy_zr_1:
	s_add_u32 s22, s20, 0x100
	v_mov_b32_e32 v2, 0
	s_addc_u32 s67, s21, 0
	s_mov_b32 s24, 0
	v_mov_b32_e32 v3, v2
	v_mov_b32_e32 v4, v2
	v_mov_b32_e32 v5, v2
	v_mov_b32_e32 v6, v2
	v_mov_b32_e32 v7, v2
	v_mov_b32_e32 v8, v2
	v_mov_b32_e32 v9, v2
	v_mov_b32_e32 v18, v2
	v_mov_b32_e32 v19, v2
	v_mov_b32_e32 v20, v2
	v_mov_b32_e32 v21, v2
	v_mov_b32_e32 v22, v2
	v_mov_b32_e32 v23, v2
	v_mov_b32_e32 v24, v2
	v_mov_b32_e32 v25, v2
	v_mov_b32_e32 v34, v2
	v_mov_b32_e32 v35, v2
	v_mov_b32_e32 v36, v2
	v_mov_b32_e32 v37, v2
	v_mov_b32_e32 v38, v2
	v_mov_b32_e32 v39, v2
	v_mov_b32_e32 v40, v2
	v_mov_b32_e32 v41, v2
	v_mov_b32_e32 v50, v2
	v_mov_b32_e32 v51, v2
	v_mov_b32_e32 v52, v2
	v_mov_b32_e32 v53, v2
	v_mov_b32_e32 v54, v2
	v_mov_b32_e32 v55, v2
	v_mov_b32_e32 v56, v2
	v_mov_b32_e32 v57, v2
	v_mov_b32_e32 v10, v2
	v_mov_b32_e32 v11, v2
	v_mov_b32_e32 v12, v2
	v_mov_b32_e32 v13, v2
	v_mov_b32_e32 v14, v2
	v_mov_b32_e32 v15, v2
	v_mov_b32_e32 v16, v2
	v_mov_b32_e32 v17, v2
	v_mov_b32_e32 v26, v2
	v_mov_b32_e32 v27, v2
	v_mov_b32_e32 v28, v2
	v_mov_b32_e32 v29, v2
	v_mov_b32_e32 v30, v2
	v_mov_b32_e32 v31, v2
	v_mov_b32_e32 v32, v2
	v_mov_b32_e32 v33, v2
	v_mov_b32_e32 v42, v2
	v_mov_b32_e32 v43, v2
	v_mov_b32_e32 v44, v2
	v_mov_b32_e32 v45, v2
	v_mov_b32_e32 v46, v2
	v_mov_b32_e32 v47, v2
	v_mov_b32_e32 v48, v2
	v_mov_b32_e32 v49, v2
	v_mov_b32_e32 v58, v2
	v_mov_b32_e32 v59, v2
	v_mov_b32_e32 v60, v2
	v_mov_b32_e32 v61, v2
	v_mov_b32_e32 v62, v2
	v_mov_b32_e32 v63, v2
	v_mov_b32_e32 v64, v2
	v_mov_b32_e32 v65, v2
	v_mov_b32_e32 v66, v2
	v_mov_b32_e32 v67, v2
	v_mov_b32_e32 v68, v2
	v_mov_b32_e32 v69, v2
	v_mov_b32_e32 v70, v2
	v_mov_b32_e32 v71, v2
	v_mov_b32_e32 v72, v2
	v_mov_b32_e32 v73, v2
	v_mov_b32_e32 v82, v2
	v_mov_b32_e32 v83, v2
	v_mov_b32_e32 v84, v2
	v_mov_b32_e32 v85, v2
	v_mov_b32_e32 v86, v2
	v_mov_b32_e32 v87, v2
	v_mov_b32_e32 v88, v2
	v_mov_b32_e32 v89, v2
	v_mov_b32_e32 v98, v2
	v_mov_b32_e32 v99, v2
	v_mov_b32_e32 v100, v2
	v_mov_b32_e32 v101, v2
	v_mov_b32_e32 v102, v2
	v_mov_b32_e32 v103, v2
	v_mov_b32_e32 v104, v2
	v_mov_b32_e32 v105, v2
	v_mov_b32_e32 v114, v2
	v_mov_b32_e32 v115, v2
	v_mov_b32_e32 v116, v2
	v_mov_b32_e32 v117, v2
	v_mov_b32_e32 v118, v2
	v_mov_b32_e32 v119, v2
	v_mov_b32_e32 v120, v2
	v_mov_b32_e32 v121, v2
	v_mov_b32_e32 v74, v2
	v_mov_b32_e32 v75, v2
	v_mov_b32_e32 v76, v2
	v_mov_b32_e32 v77, v2
	v_mov_b32_e32 v78, v2
	v_mov_b32_e32 v79, v2
	v_mov_b32_e32 v80, v2
	v_mov_b32_e32 v81, v2
	v_mov_b32_e32 v90, v2
	v_mov_b32_e32 v91, v2
	v_mov_b32_e32 v92, v2
	v_mov_b32_e32 v93, v2
	v_mov_b32_e32 v94, v2
	v_mov_b32_e32 v95, v2
	v_mov_b32_e32 v96, v2
	v_mov_b32_e32 v97, v2
	v_mov_b32_e32 v106, v2
	v_mov_b32_e32 v107, v2
	v_mov_b32_e32 v108, v2
	v_mov_b32_e32 v109, v2
	v_mov_b32_e32 v110, v2
	v_mov_b32_e32 v111, v2
	v_mov_b32_e32 v112, v2
	v_mov_b32_e32 v113, v2
	v_mov_b32_e32 v126, v2
	v_mov_b32_e32 v127, v2
	v_mov_b32_e32 v128, v2
	v_mov_b32_e32 v129, v2
	v_mov_b32_e32 v122, v2
	v_mov_b32_e32 v123, v2
	v_mov_b32_e32 v124, v2
	v_mov_b32_e32 v125, v2

;     __device__ __forceinline__ bool next(int i, Unit& u) const { return (i < na) ? a.next(i, u) : b.next(i - na, u); }
; template <class Epi, bool ALIGN_EPI = true, bool SP2 = true, bool QUARTER = false, class Sched = Order>
; __device__ __forceinline__ void gemm_phase(PG8_LAS unsigned char* lds, const Gemm g, const Sched& S, const Epi& E) {
;     ...
;     for (;;) {
;         const bool has_next = S.next(ui + 1, nxt);
;         const char* nA = has_next ? (const char*)(g.A + (size_t)nxt.z * g.zA) + (size_t)nxt.pm * tstepA : cA; const char* nB = has_next ? (const char*)(g.Bt + (size_t)nxt.z * g.zB) + (size_t)nxt.pn * tstepB : cB;
;         for (int t = 0; t < nt; t += 2) {
;             const bool last = (t == nt - 2);
;             const char* a1 = cA + (size_t)(t + 1) * kstep;
;             const char* a2 = last ? nA : cA + (size_t)(t + 2) * kstep; const char* b2 = last ? nB : cB + (size_t)(t + 2) * kstep;
;             const char* a3 = a2 + kstep; const char* b3 = b2 + kstep;
;     ...
; #pragma unroll
;         for (int a = 0; a < 2; ++a)
; #pragma unroll
;             for (int b = 0; b < 2; ++b)
; #pragma unroll
;                 for (int m = 0; m < 4; ++m)
; #pragma unroll
;                     for (int n = 0; n < 2; ++n) acc[a][b][m][n] = (f32x4){0.f, 0.f, 0.f, 0.f};
.LBB0_821:
	s_ashr_i32 s17, s16, 31
	s_lshl_b64 s[20:21], s[16:17], 17
	s_add_u32 s20, s38, s20
	s_addc_u32 s21, s39, s21
	s_ashr_i32 s19, s18, 31
	s_lshl_b64 s[24:25], s[18:19], 17
	s_add_u32 s24, s40, s24
	s_addc_u32 s25, s41, s25
	s_andn2_b64 vcc, exec, s[6:7]
	s_cbranch_vccz .Lmy_zr_2
	v_mov_b32_e32 v125, 0
	v_mov_b32_e32 v124, v125
	v_mov_b32_e32 v123, v125
	v_mov_b32_e32 v122, v125
	v_mov_b32_e32 v129, v125
	v_mov_b32_e32 v128, v125
	v_mov_b32_e32 v127, v125
	v_mov_b32_e32 v126, v125
	v_mov_b32_e32 v113, v125
	v_mov_b32_e32 v112, v125
	v_mov_b32_e32 v111, v125
	v_mov_b32_e32 v110, v125
	v_mov_b32_e32 v109, v125
	v_mov_b32_e32 v108, v125
	v_mov_b32_e32 v107, v125
	v_mov_b32_e32 v106, v125
	v_mov_b32_e32 v97, v125
	v_mov_b32_e32 v96, v125
	v_mov_b32_e32 v95, v125
	v_mov_b32_e32 v94, v125
	v_mov_b32_e32 v93, v125
	v_mov_b32_e32 v92, v125
	v_mov_b32_e32 v91, v125
	v_mov_b32_e32 v90, v125
	v_mov_b32_e32 v81, v125
	v_mov_b32_e32 v80, v125
	v_mov_b32_e32 v79, v125
	v_mov_b32_e32 v78, v125
	v_mov_b32_e32 v77, v125
	v_mov_b32_e32 v76, v125
	v_mov_b32_e32 v75, v125
	v_mov_b32_e32 v74, v125
	v_mov_b32_e32 v121, v125
	v_mov_b32_e32 v120, v125
	v_mov_b32_e32 v119, v125
	v_mov_b32_e32 v118, v125
	v_mov_b32_e32 v117, v125
	v_mov_b32_e32 v116, v125
	v_mov_b32_e32 v115, v125
	v_mov_b32_e32 v114, v125
	v_mov_b32_e32 v105, v125
	v_mov_b32_e32 v104, v125
	v_mov_b32_e32 v103, v125
	v_mov_b32_e32 v102, v125
	v_mov_b32_e32 v101, v125
	v_mov_b32_e32 v100, v125
	v_mov_b32_e32 v99, v125
	v_mov_b32_e32 v98, v125
	v_mov_b32_e32 v89, v125
	v_mov_b32_e32 v88, v125
	v_mov_b32_e32 v87, v125
	v_mov_b32_e32 v86, v125
	v_mov_b32_e32 v85, v125
	v_mov_b32_e32 v84, v125
	v_mov_b32_e32 v83, v125
	v_mov_b32_e32 v82, v125
	v_mov_b32_e32 v73, v125
	v_mov_b32_e32 v72, v125
	v_mov_b32_e32 v71, v125
	v_mov_b32_e32 v70, v125
	v_mov_b32_e32 v69, v125
	v_mov_b32_e32 v68, v125
	v_mov_b32_e32 v67, v125
	v_mov_b32_e32 v66, v125
	v_mov_b32_e32 v65, v125
	v_mov_b32_e32 v64, v125
	v_mov_b32_e32 v63, v125
	v_mov_b32_e32 v62, v125
	v_mov_b32_e32 v61, v125
	v_mov_b32_e32 v60, v125
	v_mov_b32_e32 v59, v125
	v_mov_b32_e32 v58, v125
	v_mov_b32_e32 v49, v125
	v_mov_b32_e32 v48, v125
	v_mov_b32_e32 v47, v125
	v_mov_b32_e32 v46, v125
	v_mov_b32_e32 v45, v125
	v_mov_b32_e32 v44, v125
	v_mov_b32_e32 v43, v125
	v_mov_b32_e32 v42, v125
	v_mov_b32_e32 v33, v125
	v_mov_b32_e32 v32, v125
	v_mov_b32_e32 v31, v125
	v_mov_b32_e32 v30, v125
	v_mov_b32_e32 v29, v125
	v_mov_b32_e32 v28, v125
	v_mov_b32_e32 v27, v125
	v_mov_b32_e32 v26, v125
	v_mov_b32_e32 v17, v125
	v_mov_b32_e32 v16, v125
	v_mov_b32_e32 v15, v125
	v_mov_b32_e32 v14, v125
	v_mov_b32_e32 v13, v125
	v_mov_b32_e32 v12, v125
	v_mov_b32_e32 v11, v125
	v_mov_b32_e32 v10, v125
	v_mov_b32_e32 v57, v125
	v_mov_b32_e32 v56, v125
	v_mov_b32_e32 v55, v125
	v_mov_b32_e32 v54, v125
	v_mov_b32_e32 v53, v125
	v_mov_b32_e32 v52, v125
	v_mov_b32_e32 v51, v125
	v_mov_b32_e32 v50, v125
	v_mov_b32_e32 v41, v125
	v_mov_b32_e32 v40, v125
	v_mov_b32_e32 v39, v125
	v_mov_b32_e32 v38, v125
	v_mov_b32_e32 v37, v125
	v_mov_b32_e32 v36, v125
	v_mov_b32_e32 v35, v125
	v_mov_b32_e32 v34, v125
	v_mov_b32_e32 v25, v125
	v_mov_b32_e32 v24, v125
	v_mov_b32_e32 v23, v125
	v_mov_b32_e32 v22, v125
	v_mov_b32_e32 v21, v125
	v_mov_b32_e32 v20, v125
	v_mov_b32_e32 v19, v125
	v_mov_b32_e32 v18, v125
	v_mov_b32_e32 v9, v125
	v_mov_b32_e32 v8, v125
	v_mov_b32_e32 v7, v125
	v_mov_b32_e32 v6, v125
	v_mov_b32_e32 v5, v125
	v_mov_b32_e32 v4, v125
	v_mov_b32_e32 v3, v125
	v_mov_b32_e32 v2, v125
	s_branch .LBB0_824
.Lmy_zr_2:
	s_and_b64 s[30:31], s[2:3], exec
	s_cselect_b32 s17, s21, s29
	s_cselect_b32 s19, s20, s28
	s_cselect_b32 s22, s25, s27
	s_cselect_b32 s63, s24, s26
	s_add_u32 s64, s26, 0x100
	s_addc_u32 s65, s27, 0
	s_add_u32 s26, s28, 0x10080
	v_mov_b32_e32 v2, 0
	s_addc_u32 s27, s29, 0
	s_mov_b32 s28, 0
	v_mov_b32_e32 v3, v2
	v_mov_b32_e32 v4, v2
	v_mov_b32_e32 v5, v2
	v_mov_b32_e32 v6, v2
	v_mov_b32_e32 v7, v2
	v_mov_b32_e32 v8, v2
	v_mov_b32_e32 v9, v2
	v_mov_b32_e32 v18, v2
	v_mov_b32_e32 v19, v2
	v_mov_b32_e32 v20, v2
	v_mov_b32_e32 v21, v2
	v_mov_b32_e32 v22, v2
	v_mov_b32_e32 v23, v2
	v_mov_b32_e32 v24, v2
	v_mov_b32_e32 v25, v2
	v_mov_b32_e32 v34, v2
	v_mov_b32_e32 v35, v2
	v_mov_b32_e32 v36, v2
	v_mov_b32_e32 v37, v2
	v_mov_b32_e32 v38, v2
	v_mov_b32_e32 v39, v2
	v_mov_b32_e32 v40, v2
	v_mov_b32_e32 v41, v2
	v_mov_b32_e32 v50, v2
	v_mov_b32_e32 v51, v2
	v_mov_b32_e32 v52, v2
	v_mov_b32_e32 v53, v2
	v_mov_b32_e32 v54, v2
	v_mov_b32_e32 v55, v2
	v_mov_b32_e32 v56, v2
	v_mov_b32_e32 v57, v2
	v_mov_b32_e32 v10, v2
	v_mov_b32_e32 v11, v2
	v_mov_b32_e32 v12, v2
	v_mov_b32_e32 v13, v2
	v_mov_b32_e32 v14, v2
	v_mov_b32_e32 v15, v2
	v_mov_b32_e32 v16, v2
	v_mov_b32_e32 v17, v2
	v_mov_b32_e32 v26, v2
	v_mov_b32_e32 v27, v2
	v_mov_b32_e32 v28, v2
	v_mov_b32_e32 v29, v2
	v_mov_b32_e32 v30, v2
	v_mov_b32_e32 v31, v2
	v_mov_b32_e32 v32, v2
	v_mov_b32_e32 v33, v2
	v_mov_b32_e32 v42, v2
	v_mov_b32_e32 v43, v2
	v_mov_b32_e32 v44, v2
	v_mov_b32_e32 v45, v2
	v_mov_b32_e32 v46, v2
	v_mov_b32_e32 v47, v2
	v_mov_b32_e32 v48, v2
	v_mov_b32_e32 v49, v2
	v_mov_b32_e32 v58, v2
	v_mov_b32_e32 v59, v2
	v_mov_b32_e32 v60, v2
	v_mov_b32_e32 v61, v2
	v_mov_b32_e32 v62, v2
	v_mov_b32_e32 v63, v2
	v_mov_b32_e32 v64, v2
	v_mov_b32_e32 v65, v2
	v_mov_b32_e32 v66, v2
	v_mov_b32_e32 v67, v2
	v_mov_b32_e32 v68, v2
	v_mov_b32_e32 v69, v2
	v_mov_b32_e32 v70, v2
	v_mov_b32_e32 v71, v2
	v_mov_b32_e32 v72, v2
	v_mov_b32_e32 v73, v2
	v_mov_b32_e32 v82, v2
	v_mov_b32_e32 v83, v2
	v_mov_b32_e32 v84, v2
	v_mov_b32_e32 v85, v2
	v_mov_b32_e32 v86, v2
	v_mov_b32_e32 v87, v2
	v_mov_b32_e32 v88, v2
	v_mov_b32_e32 v89, v2
	v_mov_b32_e32 v98, v2
	v_mov_b32_e32 v99, v2
	v_mov_b32_e32 v100, v2
	v_mov_b32_e32 v101, v2
	v_mov_b32_e32 v102, v2
	v_mov_b32_e32 v103, v2
	v_mov_b32_e32 v104, v2
	v_mov_b32_e32 v105, v2
	v_mov_b32_e32 v114, v2
	v_mov_b32_e32 v115, v2
	v_mov_b32_e32 v116, v2
	v_mov_b32_e32 v117, v2
	v_mov_b32_e32 v118, v2
	v_mov_b32_e32 v119, v2
	v_mov_b32_e32 v120, v2
	v_mov_b32_e32 v121, v2
	v_mov_b32_e32 v74, v2
	v_mov_b32_e32 v75, v2
	v_mov_b32_e32 v76, v2
	v_mov_b32_e32 v77, v2
	v_mov_b32_e32 v78, v2
	v_mov_b32_e32 v79, v2
	v_mov_b32_e32 v80, v2
	v_mov_b32_e32 v81, v2
	v_mov_b32_e32 v90, v2
	v_mov_b32_e32 v91, v2
	v_mov_b32_e32 v92, v2
	v_mov_b32_e32 v93, v2
	v_mov_b32_e32 v94, v2
	v_mov_b32_e32 v95, v2
	v_mov_b32_e32 v96, v2
	v_mov_b32_e32 v97, v2
	v_mov_b32_e32 v106, v2
	v_mov_b32_e32 v107, v2
	v_mov_b32_e32 v108, v2
	v_mov_b32_e32 v109, v2
	v_mov_b32_e32 v110, v2
	v_mov_b32_e32 v111, v2
	v_mov_b32_e32 v112, v2
	v_mov_b32_e32 v113, v2
	v_mov_b32_e32 v126, v2
	v_mov_b32_e32 v127, v2
	v_mov_b32_e32 v128, v2
	v_mov_b32_e32 v129, v2
	v_mov_b32_e32 v122, v2
	v_mov_b32_e32 v123, v2
	v_mov_b32_e32 v124, v2
	v_mov_b32_e32 v125, v2

;     __device__ __forceinline__ bool next(int i, Unit& u) const { return (i < na) ? a.next(i, u) : b.next(i - na, u); }
; template <class Epi, bool ALIGN_EPI = true, bool SP2 = true, bool QUARTER = false, class Sched = Order>
; __device__ __forceinline__ void gemm_phase(PG8_LAS unsigned char* lds, const Gemm g, const Sched& S, const Epi& E) {
;     ...
;     for (;;) {
;         const bool has_next = S.next(ui + 1, nxt);
;         const char* nA = has_next ? (const char*)(g.A + (size_t)nxt.z * g.zA) + (size_t)nxt.pm * tstepA : cA; const char* nB = has_next ? (const char*)(g.Bt + (size_t)nxt.z * g.zB) + (size_t)nxt.pn * tstepB : cB;
;         for (int t = 0; t < nt; t += 2) {
;             const bool last = (t == nt - 2);
;             const char* a1 = cA + (size_t)(t + 1) * kstep;
;             const char* a2 = last ? nA : cA + (size_t)(t + 2) * kstep; const char* b2 = last ? nB : cB + (size_t)(t + 2) * kstep;
;             const char* a3 = a2 + kstep; const char* b3 = b2 + kstep;
;     ...
; #pragma unroll
;         for (int a = 0; a < 2; ++a)
; #pragma unroll
;             for (int b = 0; b < 2; ++b)
; #pragma unroll
;                 for (int m = 0; m < 4; ++m)
; #pragma unroll
;                     for (int n = 0; n < 2; ++n) acc[a][b][m][n] = (f32x4){0.f, 0.f, 0.f, 0.f};
.LBB0_1564:
	s_andn2_b64 vcc, exec, s[8:9]
	s_cbranch_vccz .Lmy_zr_3
	v_mov_b32_e32 v129, 0
	v_mov_b32_e32 v128, v129
	v_mov_b32_e32 v127, v129
	v_mov_b32_e32 v126, v129
	v_mov_b32_e32 v125, v129
	v_mov_b32_e32 v124, v129
	v_mov_b32_e32 v123, v129
	v_mov_b32_e32 v122, v129
	v_mov_b32_e32 v113, v129
	v_mov_b32_e32 v112, v129
	v_mov_b32_e32 v111, v129
	v_mov_b32_e32 v110, v129
	v_mov_b32_e32 v109, v129
	v_mov_b32_e32 v108, v129
	v_mov_b32_e32 v107, v129
	v_mov_b32_e32 v106, v129
	v_mov_b32_e32 v97, v129
	v_mov_b32_e32 v96, v129
	v_mov_b32_e32 v95, v129
	v_mov_b32_e32 v94, v129
	v_mov_b32_e32 v93, v129
	v_mov_b32_e32 v92, v129
	v_mov_b32_e32 v91, v129
	v_mov_b32_e32 v90, v129
	v_mov_b32_e32 v81, v129
	v_mov_b32_e32 v80, v129
	v_mov_b32_e32 v79, v129
	v_mov_b32_e32 v78, v129
	v_mov_b32_e32 v77, v129
	v_mov_b32_e32 v76, v129
	v_mov_b32_e32 v75, v129
	v_mov_b32_e32 v74, v129
	v_mov_b32_e32 v121, v129
	v_mov_b32_e32 v120, v129
	v_mov_b32_e32 v119, v129
	v_mov_b32_e32 v118, v129
	v_mov_b32_e32 v117, v129
	v_mov_b32_e32 v116, v129
	v_mov_b32_e32 v115, v129
	v_mov_b32_e32 v114, v129
	v_mov_b32_e32 v105, v129
	v_mov_b32_e32 v104, v129
	v_mov_b32_e32 v103, v129
	v_mov_b32_e32 v102, v129
	v_mov_b32_e32 v101, v129
	v_mov_b32_e32 v100, v129
	v_mov_b32_e32 v99, v129
	v_mov_b32_e32 v98, v129
	v_mov_b32_e32 v89, v129
	v_mov_b32_e32 v88, v129
	v_mov_b32_e32 v87, v129
	v_mov_b32_e32 v86, v129
	v_mov_b32_e32 v85, v129
	v_mov_b32_e32 v84, v129
	v_mov_b32_e32 v83, v129
	v_mov_b32_e32 v82, v129
	v_mov_b32_e32 v73, v129
	v_mov_b32_e32 v72, v129
	v_mov_b32_e32 v71, v129
	v_mov_b32_e32 v70, v129
	v_mov_b32_e32 v69, v129
	v_mov_b32_e32 v68, v129
	v_mov_b32_e32 v67, v129
	v_mov_b32_e32 v66, v129
	v_mov_b32_e32 v65, v129
	v_mov_b32_e32 v64, v129
	v_mov_b32_e32 v63, v129
	v_mov_b32_e32 v62, v129
	v_mov_b32_e32 v61, v129
	v_mov_b32_e32 v60, v129
	v_mov_b32_e32 v59, v129
	v_mov_b32_e32 v58, v129
	v_mov_b32_e32 v49, v129
	v_mov_b32_e32 v48, v129
	v_mov_b32_e32 v47, v129
	v_mov_b32_e32 v46, v129
	v_mov_b32_e32 v45, v129
	v_mov_b32_e32 v44, v129
	v_mov_b32_e32 v43, v129
	v_mov_b32_e32 v42, v129
	v_mov_b32_e32 v33, v129
	v_mov_b32_e32 v32, v129
	v_mov_b32_e32 v31, v129
	v_mov_b32_e32 v30, v129
	v_mov_b32_e32 v29, v129
	v_mov_b32_e32 v28, v129
	v_mov_b32_e32 v27, v129
	v_mov_b32_e32 v26, v129
	v_mov_b32_e32 v17, v129
	v_mov_b32_e32 v16, v129
	v_mov_b32_e32 v15, v129
	v_mov_b32_e32 v14, v129
	v_mov_b32_e32 v13, v129
	v_mov_b32_e32 v12, v129
	v_mov_b32_e32 v11, v129
	v_mov_b32_e32 v10, v129
	v_mov_b32_e32 v57, v129
	v_mov_b32_e32 v56, v129
	v_mov_b32_e32 v55, v129
	v_mov_b32_e32 v54, v129
	v_mov_b32_e32 v53, v129
	v_mov_b32_e32 v52, v129
	v_mov_b32_e32 v51, v129
	v_mov_b32_e32 v50, v129
	v_mov_b32_e32 v41, v129
	v_mov_b32_e32 v40, v129
	v_mov_b32_e32 v39, v129
	v_mov_b32_e32 v38, v129
	v_mov_b32_e32 v37, v129
	v_mov_b32_e32 v36, v129
	v_mov_b32_e32 v35, v129
	v_mov_b32_e32 v34, v129
	v_mov_b32_e32 v25, v129
	v_mov_b32_e32 v24, v129
	v_mov_b32_e32 v23, v129
	v_mov_b32_e32 v22, v129
	v_mov_b32_e32 v21, v129
	v_mov_b32_e32 v20, v129
	v_mov_b32_e32 v19, v129
	v_mov_b32_e32 v18, v129
	v_mov_b32_e32 v9, v129
	v_mov_b32_e32 v8, v129
	v_mov_b32_e32 v7, v129
	v_mov_b32_e32 v6, v129
	v_mov_b32_e32 v5, v129
	v_mov_b32_e32 v4, v129
	v_mov_b32_e32 v3, v129
	v_mov_b32_e32 v2, v129
	s_branch .LBB0_1568
.Lmy_zr_3:
	s_add_u32 s22, s24, 0x100
	v_mov_b32_e32 v2, 0
	s_addc_u32 s79, s25, 0
	s_mov_b32 s26, 0
	v_mov_b32_e32 v3, v2
	v_mov_b32_e32 v4, v2
	v_mov_b32_e32 v5, v2
	v_mov_b32_e32 v6, v2
	v_mov_b32_e32 v7, v2
	v_mov_b32_e32 v8, v2
	v_mov_b32_e32 v9, v2
	v_mov_b32_e32 v18, v2
	v_mov_b32_e32 v19, v2
	v_mov_b32_e32 v20, v2
	v_mov_b32_e32 v21, v2
	v_mov_b32_e32 v22, v2
	v_mov_b32_e32 v23, v2
	v_mov_b32_e32 v24, v2
	v_mov_b32_e32 v25, v2
	v_mov_b32_e32 v34, v2
	v_mov_b32_e32 v35, v2
	v_mov_b32_e32 v36, v2
	v_mov_b32_e32 v37, v2
	v_mov_b32_e32 v38, v2
	v_mov_b32_e32 v39, v2
	v_mov_b32_e32 v40, v2
	v_mov_b32_e32 v41, v2
	v_mov_b32_e32 v50, v2
	v_mov_b32_e32 v51, v2
	v_mov_b32_e32 v52, v2
	v_mov_b32_e32 v53, v2
	v_mov_b32_e32 v54, v2
	v_mov_b32_e32 v55, v2
	v_mov_b32_e32 v56, v2
	v_mov_b32_e32 v57, v2
	v_mov_b32_e32 v10, v2
	v_mov_b32_e32 v11, v2
	v_mov_b32_e32 v12, v2
	v_mov_b32_e32 v13, v2
	v_mov_b32_e32 v14, v2
	v_mov_b32_e32 v15, v2
	v_mov_b32_e32 v16, v2
	v_mov_b32_e32 v17, v2
	v_mov_b32_e32 v26, v2
	v_mov_b32_e32 v27, v2
	v_mov_b32_e32 v28, v2
	v_mov_b32_e32 v29, v2
	v_mov_b32_e32 v30, v2
	v_mov_b32_e32 v31, v2
	v_mov_b32_e32 v32, v2
	v_mov_b32_e32 v33, v2
	v_mov_b32_e32 v42, v2
	v_mov_b32_e32 v43, v2
	v_mov_b32_e32 v44, v2
	v_mov_b32_e32 v45, v2
	v_mov_b32_e32 v46, v2
	v_mov_b32_e32 v47, v2
	v_mov_b32_e32 v48, v2
	v_mov_b32_e32 v49, v2
	v_mov_b32_e32 v58, v2
	v_mov_b32_e32 v59, v2
	v_mov_b32_e32 v60, v2
	v_mov_b32_e32 v61, v2
	v_mov_b32_e32 v62, v2
	v_mov_b32_e32 v63, v2
	v_mov_b32_e32 v64, v2
	v_mov_b32_e32 v65, v2
	v_mov_b32_e32 v66, v2
	v_mov_b32_e32 v67, v2
	v_mov_b32_e32 v68, v2
	v_mov_b32_e32 v69, v2
	v_mov_b32_e32 v70, v2
	v_mov_b32_e32 v71, v2
	v_mov_b32_e32 v72, v2
	v_mov_b32_e32 v73, v2
	v_mov_b32_e32 v82, v2
	v_mov_b32_e32 v83, v2
	v_mov_b32_e32 v84, v2
	v_mov_b32_e32 v85, v2
	v_mov_b32_e32 v86, v2
	v_mov_b32_e32 v87, v2
	v_mov_b32_e32 v88, v2
	v_mov_b32_e32 v89, v2
	v_mov_b32_e32 v98, v2
	v_mov_b32_e32 v99, v2
	v_mov_b32_e32 v100, v2
	v_mov_b32_e32 v101, v2
	v_mov_b32_e32 v102, v2
	v_mov_b32_e32 v103, v2
	v_mov_b32_e32 v104, v2
	v_mov_b32_e32 v105, v2
	v_mov_b32_e32 v114, v2
	v_mov_b32_e32 v115, v2
	v_mov_b32_e32 v116, v2
	v_mov_b32_e32 v117, v2
	v_mov_b32_e32 v118, v2
	v_mov_b32_e32 v119, v2
	v_mov_b32_e32 v120, v2
	v_mov_b32_e32 v121, v2
	v_mov_b32_e32 v74, v2
	v_mov_b32_e32 v75, v2
	v_mov_b32_e32 v76, v2
	v_mov_b32_e32 v77, v2
	v_mov_b32_e32 v78, v2
	v_mov_b32_e32 v79, v2
	v_mov_b32_e32 v80, v2
	v_mov_b32_e32 v81, v2
	v_mov_b32_e32 v90, v2
	v_mov_b32_e32 v91, v2
	v_mov_b32_e32 v92, v2
	v_mov_b32_e32 v93, v2
	v_mov_b32_e32 v94, v2
	v_mov_b32_e32 v95, v2
	v_mov_b32_e32 v96, v2
	v_mov_b32_e32 v97, v2
	v_mov_b32_e32 v106, v2
	v_mov_b32_e32 v107, v2
	v_mov_b32_e32 v108, v2
	v_mov_b32_e32 v109, v2
	v_mov_b32_e32 v110, v2
	v_mov_b32_e32 v111, v2
	v_mov_b32_e32 v112, v2
	v_mov_b32_e32 v113, v2
	v_mov_b32_e32 v122, v2
	v_mov_b32_e32 v123, v2
	v_mov_b32_e32 v124, v2
	v_mov_b32_e32 v125, v2
	v_mov_b32_e32 v126, v2
	v_mov_b32_e32 v127, v2
	v_mov_b32_e32 v128, v2
	v_mov_b32_e32 v129, v2

;     __device__ __forceinline__ bool next(int i, Unit& u) const { return (i < na) ? a.next(i, u) : b.next(i - na, u); }
; template <class Epi, bool ALIGN_EPI = true, bool SP2 = true, bool QUARTER = false, class Sched = Order>
; __device__ __forceinline__ void gemm_phase(PG8_LAS unsigned char* lds, const Gemm g, const Sched& S, const Epi& E) {
;     ...
;     for (;;) {
;         const bool has_next = S.next(ui + 1, nxt);
;         const char* nA = has_next ? (const char*)(g.A + (size_t)nxt.z * g.zA) + (size_t)nxt.pm * tstepA : cA; const char* nB = has_next ? (const char*)(g.Bt + (size_t)nxt.z * g.zB) + (size_t)nxt.pn * tstepB : cB;
;         for (int t = 0; t < nt; t += 2) {
;             const bool last = (t == nt - 2);
;             const char* a1 = cA + (size_t)(t + 1) * kstep;
;             const char* a2 = last ? nA : cA + (size_t)(t + 2) * kstep; const char* b2 = last ? nB : cB + (size_t)(t + 2) * kstep;
;             const char* a3 = a2 + kstep; const char* b3 = b2 + kstep;
;     ...
; #pragma unroll
;         for (int a = 0; a < 2; ++a)
; #pragma unroll
;             for (int b = 0; b < 2; ++b)
; #pragma unroll
;                 for (int m = 0; m < 4; ++m)
; #pragma unroll
;                     for (int n = 0; n < 2; ++n) acc[a][b][m][n] = (f32x4){0.f, 0.f, 0.f, 0.f};
.LBB0_1675:
	s_ashr_i32 s17, s16, 31
	s_lshl_b64 s[20:21], s[16:17], 18
	s_add_u32 s20, s72, s20
	s_addc_u32 s21, s73, s21
	s_ashr_i32 s19, s18, 31
	s_lshl_b64 s[24:25], s[18:19], 18
	s_add_u32 s24, s74, s24
	s_addc_u32 s25, s75, s25
	s_andn2_b64 vcc, exec, s[6:7]
	s_cbranch_vccz .Lmy_zr_4
	v_mov_b32_e32 v125, 0
	v_mov_b32_e32 v124, v125
	v_mov_b32_e32 v123, v125
	v_mov_b32_e32 v122, v125
	v_mov_b32_e32 v129, v125
	v_mov_b32_e32 v128, v125
	v_mov_b32_e32 v127, v125
	v_mov_b32_e32 v126, v125
	v_mov_b32_e32 v113, v125
	v_mov_b32_e32 v112, v125
	v_mov_b32_e32 v111, v125
	v_mov_b32_e32 v110, v125
	v_mov_b32_e32 v109, v125
	v_mov_b32_e32 v108, v125
	v_mov_b32_e32 v107, v125
	v_mov_b32_e32 v106, v125
	v_mov_b32_e32 v97, v125
	v_mov_b32_e32 v96, v125
	v_mov_b32_e32 v95, v125
	v_mov_b32_e32 v94, v125
	v_mov_b32_e32 v93, v125
	v_mov_b32_e32 v92, v125
	v_mov_b32_e32 v91, v125
	v_mov_b32_e32 v90, v125
	v_mov_b32_e32 v81, v125
	v_mov_b32_e32 v80, v125
	v_mov_b32_e32 v79, v125
	v_mov_b32_e32 v78, v125
	v_mov_b32_e32 v77, v125
	v_mov_b32_e32 v76, v125
	v_mov_b32_e32 v75, v125
	v_mov_b32_e32 v74, v125
	v_mov_b32_e32 v121, v125
	v_mov_b32_e32 v120, v125
	v_mov_b32_e32 v119, v125
	v_mov_b32_e32 v118, v125
	v_mov_b32_e32 v117, v125
	v_mov_b32_e32 v116, v125
	v_mov_b32_e32 v115, v125
	v_mov_b32_e32 v114, v125
	v_mov_b32_e32 v105, v125
	v_mov_b32_e32 v104, v125
	v_mov_b32_e32 v103, v125
	v_mov_b32_e32 v102, v125
	v_mov_b32_e32 v101, v125
	v_mov_b32_e32 v100, v125
	v_mov_b32_e32 v99, v125
	v_mov_b32_e32 v98, v125
	v_mov_b32_e32 v89, v125
	v_mov_b32_e32 v88, v125
	v_mov_b32_e32 v87, v125
	v_mov_b32_e32 v86, v125
	v_mov_b32_e32 v85, v125
	v_mov_b32_e32 v84, v125
	v_mov_b32_e32 v83, v125
	v_mov_b32_e32 v82, v125
	v_mov_b32_e32 v73, v125
	v_mov_b32_e32 v72, v125
	v_mov_b32_e32 v71, v125
	v_mov_b32_e32 v70, v125
	v_mov_b32_e32 v69, v125
	v_mov_b32_e32 v68, v125
	v_mov_b32_e32 v67, v125
	v_mov_b32_e32 v66, v125
	v_mov_b32_e32 v65, v125
	v_mov_b32_e32 v64, v125
	v_mov_b32_e32 v63, v125
	v_mov_b32_e32 v62, v125
	v_mov_b32_e32 v61, v125
	v_mov_b32_e32 v60, v125
	v_mov_b32_e32 v59, v125
	v_mov_b32_e32 v58, v125
	v_mov_b32_e32 v49, v125
	v_mov_b32_e32 v48, v125
	v_mov_b32_e32 v47, v125
	v_mov_b32_e32 v46, v125
	v_mov_b32_e32 v45, v125
	v_mov_b32_e32 v44, v125
	v_mov_b32_e32 v43, v125
	v_mov_b32_e32 v42, v125
	v_mov_b32_e32 v33, v125
	v_mov_b32_e32 v32, v125
	v_mov_b32_e32 v31, v125
	v_mov_b32_e32 v30, v125
	v_mov_b32_e32 v29, v125
	v_mov_b32_e32 v28, v125
	v_mov_b32_e32 v27, v125
	v_mov_b32_e32 v26, v125
	v_mov_b32_e32 v17, v125
	v_mov_b32_e32 v16, v125
	v_mov_b32_e32 v15, v125
	v_mov_b32_e32 v14, v125
	v_mov_b32_e32 v13, v125
	v_mov_b32_e32 v12, v125
	v_mov_b32_e32 v11, v125
	v_mov_b32_e32 v10, v125
	v_mov_b32_e32 v57, v125
	v_mov_b32_e32 v56, v125
	v_mov_b32_e32 v55, v125
	v_mov_b32_e32 v54, v125
	v_mov_b32_e32 v53, v125
	v_mov_b32_e32 v52, v125
	v_mov_b32_e32 v51, v125
	v_mov_b32_e32 v50, v125
	v_mov_b32_e32 v41, v125
	v_mov_b32_e32 v40, v125
	v_mov_b32_e32 v39, v125
	v_mov_b32_e32 v38, v125
	v_mov_b32_e32 v37, v125
	v_mov_b32_e32 v36, v125
	v_mov_b32_e32 v35, v125
	v_mov_b32_e32 v34, v125
	v_mov_b32_e32 v25, v125
	v_mov_b32_e32 v24, v125
	v_mov_b32_e32 v23, v125
	v_mov_b32_e32 v22, v125
	v_mov_b32_e32 v21, v125
	v_mov_b32_e32 v20, v125
	v_mov_b32_e32 v19, v125
	v_mov_b32_e32 v18, v125
	v_mov_b32_e32 v9, v125
	v_mov_b32_e32 v8, v125
	v_mov_b32_e32 v7, v125
	v_mov_b32_e32 v6, v125
	v_mov_b32_e32 v5, v125
	v_mov_b32_e32 v4, v125
	v_mov_b32_e32 v3, v125
	v_mov_b32_e32 v2, v125
	s_branch .LBB0_1678
.Lmy_zr_4:
	s_and_b64 s[34:35], s[2:3], exec
	s_cselect_b32 s17, s21, s31
	s_cselect_b32 s19, s20, s30
	s_cselect_b32 s22, s25, s29
	s_cselect_b32 s64, s24, s28
	s_add_u32 s65, s28, 0x100
	s_addc_u32 s76, s29, 0
	s_add_u32 s28, s30, 0x20080
	v_mov_b32_e32 v2, 0
	s_addc_u32 s29, s31, 0
	s_mov_b32 s30, 0
	v_mov_b32_e32 v3, v2
	v_mov_b32_e32 v4, v2
	v_mov_b32_e32 v5, v2
	v_mov_b32_e32 v6, v2
	v_mov_b32_e32 v7, v2
	v_mov_b32_e32 v8, v2
	v_mov_b32_e32 v9, v2
	v_mov_b32_e32 v18, v2
	v_mov_b32_e32 v19, v2
	v_mov_b32_e32 v20, v2
	v_mov_b32_e32 v21, v2
	v_mov_b32_e32 v22, v2
	v_mov_b32_e32 v23, v2
	v_mov_b32_e32 v24, v2
	v_mov_b32_e32 v25, v2
	v_mov_b32_e32 v34, v2
	v_mov_b32_e32 v35, v2
	v_mov_b32_e32 v36, v2
	v_mov_b32_e32 v37, v2
	v_mov_b32_e32 v38, v2
	v_mov_b32_e32 v39, v2
	v_mov_b32_e32 v40, v2
	v_mov_b32_e32 v41, v2
	v_mov_b32_e32 v50, v2
	v_mov_b32_e32 v51, v2
	v_mov_b32_e32 v52, v2
	v_mov_b32_e32 v53, v2
	v_mov_b32_e32 v54, v2
	v_mov_b32_e32 v55, v2
	v_mov_b32_e32 v56, v2
	v_mov_b32_e32 v57, v2
	v_mov_b32_e32 v10, v2
	v_mov_b32_e32 v11, v2
	v_mov_b32_e32 v12, v2
	v_mov_b32_e32 v13, v2
	v_mov_b32_e32 v14, v2
	v_mov_b32_e32 v15, v2
	v_mov_b32_e32 v16, v2
	v_mov_b32_e32 v17, v2
	v_mov_b32_e32 v26, v2
	v_mov_b32_e32 v27, v2
	v_mov_b32_e32 v28, v2
	v_mov_b32_e32 v29, v2
	v_mov_b32_e32 v30, v2
	v_mov_b32_e32 v31, v2
	v_mov_b32_e32 v32, v2
	v_mov_b32_e32 v33, v2
	v_mov_b32_e32 v42, v2
	v_mov_b32_e32 v43, v2
	v_mov_b32_e32 v44, v2
	v_mov_b32_e32 v45, v2
	v_mov_b32_e32 v46, v2
	v_mov_b32_e32 v47, v2
	v_mov_b32_e32 v48, v2
	v_mov_b32_e32 v49, v2
	v_mov_b32_e32 v58, v2
	v_mov_b32_e32 v59, v2
	v_mov_b32_e32 v60, v2
	v_mov_b32_e32 v61, v2
	v_mov_b32_e32 v62, v2
	v_mov_b32_e32 v63, v2
	v_mov_b32_e32 v64, v2
	v_mov_b32_e32 v65, v2
	v_mov_b32_e32 v66, v2
	v_mov_b32_e32 v67, v2
	v_mov_b32_e32 v68, v2
	v_mov_b32_e32 v69, v2
	v_mov_b32_e32 v70, v2
	v_mov_b32_e32 v71, v2
	v_mov_b32_e32 v72, v2
	v_mov_b32_e32 v73, v2
	v_mov_b32_e32 v82, v2
	v_mov_b32_e32 v83, v2
	v_mov_b32_e32 v84, v2
	v_mov_b32_e32 v85, v2
	v_mov_b32_e32 v86, v2
	v_mov_b32_e32 v87, v2
	v_mov_b32_e32 v88, v2
	v_mov_b32_e32 v89, v2
	v_mov_b32_e32 v98, v2
	v_mov_b32_e32 v99, v2
	v_mov_b32_e32 v100, v2
	v_mov_b32_e32 v101, v2
	v_mov_b32_e32 v102, v2
	v_mov_b32_e32 v103, v2
	v_mov_b32_e32 v104, v2
	v_mov_b32_e32 v105, v2
	v_mov_b32_e32 v114, v2
	v_mov_b32_e32 v115, v2
	v_mov_b32_e32 v116, v2
	v_mov_b32_e32 v117, v2
	v_mov_b32_e32 v118, v2
	v_mov_b32_e32 v119, v2
	v_mov_b32_e32 v120, v2
	v_mov_b32_e32 v121, v2
	v_mov_b32_e32 v74, v2
	v_mov_b32_e32 v75, v2
	v_mov_b32_e32 v76, v2
	v_mov_b32_e32 v77, v2
	v_mov_b32_e32 v78, v2
	v_mov_b32_e32 v79, v2
	v_mov_b32_e32 v80, v2
	v_mov_b32_e32 v81, v2
	v_mov_b32_e32 v90, v2
	v_mov_b32_e32 v91, v2
	v_mov_b32_e32 v92, v2
	v_mov_b32_e32 v93, v2
	v_mov_b32_e32 v94, v2
	v_mov_b32_e32 v95, v2
	v_mov_b32_e32 v96, v2
	v_mov_b32_e32 v97, v2
	v_mov_b32_e32 v106, v2
	v_mov_b32_e32 v107, v2
	v_mov_b32_e32 v108, v2
	v_mov_b32_e32 v109, v2
	v_mov_b32_e32 v110, v2
	v_mov_b32_e32 v111, v2
	v_mov_b32_e32 v112, v2
	v_mov_b32_e32 v113, v2
	v_mov_b32_e32 v126, v2
	v_mov_b32_e32 v127, v2
	v_mov_b32_e32 v128, v2
	v_mov_b32_e32 v129, v2
	v_mov_b32_e32 v122, v2
	v_mov_b32_e32 v123, v2
	v_mov_b32_e32 v124, v2
	v_mov_b32_e32 v125, v2

;     __device__ __forceinline__ bool next(int i, Unit& u) const { return (i < na) ? a.next(i, u) : b.next(i - na, u); }
; template <class Epi, bool ALIGN_EPI = true, bool SP2 = true, bool QUARTER = false, class Sched = Order>
; __device__ __forceinline__ void gemm_phase(PG8_LAS unsigned char* lds, const Gemm g, const Sched& S, const Epi& E) {
;     ...
;     for (;;) {
;         const bool has_next = S.next(ui + 1, nxt);
;         const char* nA = has_next ? (const char*)(g.A + (size_t)nxt.z * g.zA) + (size_t)nxt.pm * tstepA : cA; const char* nB = has_next ? (const char*)(g.Bt + (size_t)nxt.z * g.zB) + (size_t)nxt.pn * tstepB : cB;
;         for (int t = 0; t < nt; t += 2) {
;             const bool last = (t == nt - 2);
;             const char* a1 = cA + (size_t)(t + 1) * kstep;
;             const char* a2 = last ? nA : cA + (size_t)(t + 2) * kstep; const char* b2 = last ? nB : cB + (size_t)(t + 2) * kstep;
;             const char* a3 = a2 + kstep; const char* b3 = b2 + kstep;
;     ...
; #pragma unroll
;         for (int a = 0; a < 2; ++a)
; #pragma unroll
;             for (int b = 0; b < 2; ++b)
; #pragma unroll
;                 for (int m = 0; m < 4; ++m)
; #pragma unroll
;                     for (int n = 0; n < 2; ++n) acc[a][b][m][n] = (f32x4){0.f, 0.f, 0.f, 0.f};
.LBB0_2025:
	s_ashr_i32 s21, s20, 31
	s_lshl_b64 s[22:23], s[20:21], 18
	s_add_u32 s30, s33, s22
	s_addc_u32 s31, s72, s23
	s_ashr_i32 s29, s28, 31
	s_lshl_b64 s[22:23], s[28:29], 18
	s_add_u32 s36, s73, s22
	s_addc_u32 s37, s74, s23
	s_andn2_b64 vcc, exec, s[8:9]
	s_cbranch_vccz .Lmy_zr_5
	v_mov_b32_e32 v125, 0
	v_mov_b32_e32 v124, v125
	v_mov_b32_e32 v123, v125
	v_mov_b32_e32 v122, v125
	v_mov_b32_e32 v129, v125
	v_mov_b32_e32 v128, v125
	v_mov_b32_e32 v127, v125
	v_mov_b32_e32 v126, v125
	v_mov_b32_e32 v113, v125
	v_mov_b32_e32 v112, v125
	v_mov_b32_e32 v111, v125
	v_mov_b32_e32 v110, v125
	v_mov_b32_e32 v109, v125
	v_mov_b32_e32 v108, v125
	v_mov_b32_e32 v107, v125
	v_mov_b32_e32 v106, v125
	v_mov_b32_e32 v97, v125
	v_mov_b32_e32 v96, v125
	v_mov_b32_e32 v95, v125
	v_mov_b32_e32 v94, v125
	v_mov_b32_e32 v93, v125
	v_mov_b32_e32 v92, v125
	v_mov_b32_e32 v91, v125
	v_mov_b32_e32 v90, v125
	v_mov_b32_e32 v81, v125
	v_mov_b32_e32 v80, v125
	v_mov_b32_e32 v79, v125
	v_mov_b32_e32 v78, v125
	v_mov_b32_e32 v77, v125
	v_mov_b32_e32 v76, v125
	v_mov_b32_e32 v75, v125
	v_mov_b32_e32 v74, v125
	v_mov_b32_e32 v121, v125
	v_mov_b32_e32 v120, v125
	v_mov_b32_e32 v119, v125
	v_mov_b32_e32 v118, v125
	v_mov_b32_e32 v117, v125
	v_mov_b32_e32 v116, v125
	v_mov_b32_e32 v115, v125
	v_mov_b32_e32 v114, v125
	v_mov_b32_e32 v105, v125
	v_mov_b32_e32 v104, v125
	v_mov_b32_e32 v103, v125
	v_mov_b32_e32 v102, v125
	v_mov_b32_e32 v101, v125
	v_mov_b32_e32 v100, v125
	v_mov_b32_e32 v99, v125
	v_mov_b32_e32 v98, v125
	v_mov_b32_e32 v89, v125
	v_mov_b32_e32 v88, v125
	v_mov_b32_e32 v87, v125
	v_mov_b32_e32 v86, v125
	v_mov_b32_e32 v85, v125
	v_mov_b32_e32 v84, v125
	v_mov_b32_e32 v83, v125
	v_mov_b32_e32 v82, v125
	v_mov_b32_e32 v73, v125
	v_mov_b32_e32 v72, v125
	v_mov_b32_e32 v71, v125
	v_mov_b32_e32 v70, v125
	v_mov_b32_e32 v69, v125
	v_mov_b32_e32 v68, v125
	v_mov_b32_e32 v67, v125
	v_mov_b32_e32 v66, v125
	v_mov_b32_e32 v65, v125
	v_mov_b32_e32 v64, v125
	v_mov_b32_e32 v63, v125
	v_mov_b32_e32 v62, v125
	v_mov_b32_e32 v61, v125
	v_mov_b32_e32 v60, v125
	v_mov_b32_e32 v59, v125
	v_mov_b32_e32 v58, v125
	v_mov_b32_e32 v49, v125
	v_mov_b32_e32 v48, v125
	v_mov_b32_e32 v47, v125
	v_mov_b32_e32 v46, v125
	v_mov_b32_e32 v45, v125
	v_mov_b32_e32 v44, v125
	v_mov_b32_e32 v43, v125
	v_mov_b32_e32 v42, v125
	v_mov_b32_e32 v33, v125
	v_mov_b32_e32 v32, v125
	v_mov_b32_e32 v31, v125
	v_mov_b32_e32 v30, v125
	v_mov_b32_e32 v29, v125
	v_mov_b32_e32 v28, v125
	v_mov_b32_e32 v27, v125
	v_mov_b32_e32 v26, v125
	v_mov_b32_e32 v17, v125
	v_mov_b32_e32 v16, v125
	v_mov_b32_e32 v15, v125
	v_mov_b32_e32 v14, v125
	v_mov_b32_e32 v13, v125
	v_mov_b32_e32 v12, v125
	v_mov_b32_e32 v11, v125
	v_mov_b32_e32 v10, v125
	v_mov_b32_e32 v57, v125
	v_mov_b32_e32 v56, v125
	v_mov_b32_e32 v55, v125
	v_mov_b32_e32 v54, v125
	v_mov_b32_e32 v53, v125
	v_mov_b32_e32 v52, v125
	v_mov_b32_e32 v51, v125
	v_mov_b32_e32 v50, v125
	v_mov_b32_e32 v41, v125
	v_mov_b32_e32 v40, v125
	v_mov_b32_e32 v39, v125
	v_mov_b32_e32 v38, v125
	v_mov_b32_e32 v37, v125
	v_mov_b32_e32 v36, v125
	v_mov_b32_e32 v35, v125
	v_mov_b32_e32 v34, v125
	v_mov_b32_e32 v25, v125
	v_mov_b32_e32 v24, v125
	v_mov_b32_e32 v23, v125
	v_mov_b32_e32 v22, v125
	v_mov_b32_e32 v21, v125
	v_mov_b32_e32 v20, v125
	v_mov_b32_e32 v19, v125
	v_mov_b32_e32 v18, v125
	v_mov_b32_e32 v9, v125
	v_mov_b32_e32 v8, v125
	v_mov_b32_e32 v7, v125
	v_mov_b32_e32 v6, v125
	v_mov_b32_e32 v5, v125
	v_mov_b32_e32 v4, v125
	v_mov_b32_e32 v3, v125
	v_mov_b32_e32 v2, v125
	s_branch .LBB0_2028
.Lmy_zr_5:
	s_and_b64 s[22:23], s[2:3], exec
	s_cselect_b32 s21, s31, s27
	s_cselect_b32 s22, s30, s26
	s_cselect_b32 s23, s37, s25
	s_cselect_b32 s29, s36, s24
	s_add_u32 s66, s24, 0x100
	s_addc_u32 s67, s25, 0
	s_add_u32 s24, s26, 0x20080
	v_mov_b32_e32 v2, 0
	s_addc_u32 s25, s27, 0
	s_mov_b32 s26, 0
	v_mov_b32_e32 v3, v2
	v_mov_b32_e32 v4, v2
	v_mov_b32_e32 v5, v2
	v_mov_b32_e32 v6, v2
	v_mov_b32_e32 v7, v2
	v_mov_b32_e32 v8, v2
	v_mov_b32_e32 v9, v2
	v_mov_b32_e32 v18, v2
	v_mov_b32_e32 v19, v2
	v_mov_b32_e32 v20, v2
	v_mov_b32_e32 v21, v2
	v_mov_b32_e32 v22, v2
	v_mov_b32_e32 v23, v2
	v_mov_b32_e32 v24, v2
	v_mov_b32_e32 v25, v2
	v_mov_b32_e32 v34, v2
	v_mov_b32_e32 v35, v2
	v_mov_b32_e32 v36, v2
	v_mov_b32_e32 v37, v2
	v_mov_b32_e32 v38, v2
	v_mov_b32_e32 v39, v2
	v_mov_b32_e32 v40, v2
	v_mov_b32_e32 v41, v2
	v_mov_b32_e32 v50, v2
	v_mov_b32_e32 v51, v2
	v_mov_b32_e32 v52, v2
	v_mov_b32_e32 v53, v2
	v_mov_b32_e32 v54, v2
	v_mov_b32_e32 v55, v2
	v_mov_b32_e32 v56, v2
	v_mov_b32_e32 v57, v2
	v_mov_b32_e32 v10, v2
	v_mov_b32_e32 v11, v2
	v_mov_b32_e32 v12, v2
	v_mov_b32_e32 v13, v2
	v_mov_b32_e32 v14, v2
	v_mov_b32_e32 v15, v2
	v_mov_b32_e32 v16, v2
	v_mov_b32_e32 v17, v2
	v_mov_b32_e32 v26, v2
	v_mov_b32_e32 v27, v2
	v_mov_b32_e32 v28, v2
	v_mov_b32_e32 v29, v2
	v_mov_b32_e32 v30, v2
	v_mov_b32_e32 v31, v2
	v_mov_b32_e32 v32, v2
	v_mov_b32_e32 v33, v2
	v_mov_b32_e32 v42, v2
	v_mov_b32_e32 v43, v2
	v_mov_b32_e32 v44, v2
	v_mov_b32_e32 v45, v2
	v_mov_b32_e32 v46, v2
	v_mov_b32_e32 v47, v2
	v_mov_b32_e32 v48, v2
	v_mov_b32_e32 v49, v2
	v_mov_b32_e32 v58, v2
	v_mov_b32_e32 v59, v2
	v_mov_b32_e32 v60, v2
	v_mov_b32_e32 v61, v2
	v_mov_b32_e32 v62, v2
	v_mov_b32_e32 v63, v2
	v_mov_b32_e32 v64, v2
	v_mov_b32_e32 v65, v2
	v_mov_b32_e32 v66, v2
	v_mov_b32_e32 v67, v2
	v_mov_b32_e32 v68, v2
	v_mov_b32_e32 v69, v2
	v_mov_b32_e32 v70, v2
	v_mov_b32_e32 v71, v2
	v_mov_b32_e32 v72, v2
	v_mov_b32_e32 v73, v2
	v_mov_b32_e32 v82, v2
	v_mov_b32_e32 v83, v2
	v_mov_b32_e32 v84, v2
	v_mov_b32_e32 v85, v2
	v_mov_b32_e32 v86, v2
	v_mov_b32_e32 v87, v2
	v_mov_b32_e32 v88, v2
	v_mov_b32_e32 v89, v2
	v_mov_b32_e32 v98, v2
	v_mov_b32_e32 v99, v2
	v_mov_b32_e32 v100, v2
	v_mov_b32_e32 v101, v2
	v_mov_b32_e32 v102, v2
	v_mov_b32_e32 v103, v2
	v_mov_b32_e32 v104, v2
	v_mov_b32_e32 v105, v2
	v_mov_b32_e32 v114, v2
	v_mov_b32_e32 v115, v2
	v_mov_b32_e32 v116, v2
	v_mov_b32_e32 v117, v2
	v_mov_b32_e32 v118, v2
	v_mov_b32_e32 v119, v2
	v_mov_b32_e32 v120, v2
	v_mov_b32_e32 v121, v2
	v_mov_b32_e32 v74, v2
	v_mov_b32_e32 v75, v2
	v_mov_b32_e32 v76, v2
	v_mov_b32_e32 v77, v2
	v_mov_b32_e32 v78, v2
	v_mov_b32_e32 v79, v2
	v_mov_b32_e32 v80, v2
	v_mov_b32_e32 v81, v2
	v_mov_b32_e32 v90, v2
	v_mov_b32_e32 v91, v2
	v_mov_b32_e32 v92, v2
	v_mov_b32_e32 v93, v2
	v_mov_b32_e32 v94, v2
	v_mov_b32_e32 v95, v2
	v_mov_b32_e32 v96, v2
	v_mov_b32_e32 v97, v2
	v_mov_b32_e32 v106, v2
	v_mov_b32_e32 v107, v2
	v_mov_b32_e32 v108, v2
	v_mov_b32_e32 v109, v2
	v_mov_b32_e32 v110, v2
	v_mov_b32_e32 v111, v2
	v_mov_b32_e32 v112, v2
	v_mov_b32_e32 v113, v2
	v_mov_b32_e32 v126, v2
	v_mov_b32_e32 v127, v2
	v_mov_b32_e32 v128, v2
	v_mov_b32_e32 v129, v2
	v_mov_b32_e32 v122, v2
	v_mov_b32_e32 v123, v2
	v_mov_b32_e32 v124, v2
	v_mov_b32_e32 v125, v2

;     __device__ __forceinline__ bool next(int i, Unit& u) const { return (i < na) ? a.next(i, u) : b.next(i - na, u); }
; template <class Epi, bool ALIGN_EPI = true, bool SP2 = true, bool QUARTER = false, class Sched = Order>
; __device__ __forceinline__ void gemm_phase(PG8_LAS unsigned char* lds, const Gemm g, const Sched& S, const Epi& E) {
;     ...
;     for (;;) {
;         const bool has_next = S.next(ui + 1, nxt);
;         const char* nA = has_next ? (const char*)(g.A + (size_t)nxt.z * g.zA) + (size_t)nxt.pm * tstepA : cA; const char* nB = has_next ? (const char*)(g.Bt + (size_t)nxt.z * g.zB) + (size_t)nxt.pn * tstepB : cB;
;         for (int t = 0; t < nt; t += 2) {
;             const bool last = (t == nt - 2);
;             const char* a1 = cA + (size_t)(t + 1) * kstep;
;             const char* a2 = last ? nA : cA + (size_t)(t + 2) * kstep; const char* b2 = last ? nB : cB + (size_t)(t + 2) * kstep;
;             const char* a3 = a2 + kstep; const char* b3 = b2 + kstep;
;     ...
; #pragma unroll
;         for (int a = 0; a < 2; ++a)
; #pragma unroll
;             for (int b = 0; b < 2; ++b)
; #pragma unroll
;                 for (int m = 0; m < 4; ++m)
; #pragma unroll
;                     for (int n = 0; n < 2; ++n) acc[a][b][m][n] = (f32x4){0.f, 0.f, 0.f, 0.f};
.LBB0_2265:
	s_ashr_i32 s31, s30, 31
	s_lshl_b64 s[22:23], s[30:31], 19
	s_add_u32 s42, s33, s22
	s_addc_u32 s43, s66, s23
	s_ashr_i32 s37, s36, 31
	s_lshl_b64 s[22:23], s[36:37], 19
	s_add_u32 s38, s67, s22
	s_addc_u32 s39, s72, s23
	s_andn2_b64 vcc, exec, s[20:21]
	s_cbranch_vccz .Lmy_zr_6
	v_mov_b32_e32 v125, 0
	v_mov_b32_e32 v124, v125
	v_mov_b32_e32 v123, v125
	v_mov_b32_e32 v122, v125
	v_mov_b32_e32 v129, v125
	v_mov_b32_e32 v128, v125
	v_mov_b32_e32 v127, v125
	v_mov_b32_e32 v126, v125
	v_mov_b32_e32 v113, v125
	v_mov_b32_e32 v112, v125
	v_mov_b32_e32 v111, v125
	v_mov_b32_e32 v110, v125
	v_mov_b32_e32 v109, v125
	v_mov_b32_e32 v108, v125
	v_mov_b32_e32 v107, v125
	v_mov_b32_e32 v106, v125
	v_mov_b32_e32 v97, v125
	v_mov_b32_e32 v96, v125
	v_mov_b32_e32 v95, v125
	v_mov_b32_e32 v94, v125
	v_mov_b32_e32 v93, v125
	v_mov_b32_e32 v92, v125
	v_mov_b32_e32 v91, v125
	v_mov_b32_e32 v90, v125
	v_mov_b32_e32 v81, v125
	v_mov_b32_e32 v80, v125
	v_mov_b32_e32 v79, v125
	v_mov_b32_e32 v78, v125
	v_mov_b32_e32 v77, v125
	v_mov_b32_e32 v76, v125
	v_mov_b32_e32 v75, v125
	v_mov_b32_e32 v74, v125
	v_mov_b32_e32 v121, v125
	v_mov_b32_e32 v120, v125
	v_mov_b32_e32 v119, v125
	v_mov_b32_e32 v118, v125
	v_mov_b32_e32 v117, v125
	v_mov_b32_e32 v116, v125
	v_mov_b32_e32 v115, v125
	v_mov_b32_e32 v114, v125
	v_mov_b32_e32 v105, v125
	v_mov_b32_e32 v104, v125
	v_mov_b32_e32 v103, v125
	v_mov_b32_e32 v102, v125
	v_mov_b32_e32 v101, v125
	v_mov_b32_e32 v100, v125
	v_mov_b32_e32 v99, v125
	v_mov_b32_e32 v98, v125
	v_mov_b32_e32 v89, v125
	v_mov_b32_e32 v88, v125
	v_mov_b32_e32 v87, v125
	v_mov_b32_e32 v86, v125
	v_mov_b32_e32 v85, v125
	v_mov_b32_e32 v84, v125
	v_mov_b32_e32 v83, v125
	v_mov_b32_e32 v82, v125
	v_mov_b32_e32 v73, v125
	v_mov_b32_e32 v72, v125
	v_mov_b32_e32 v71, v125
	v_mov_b32_e32 v70, v125
	v_mov_b32_e32 v69, v125
	v_mov_b32_e32 v68, v125
	v_mov_b32_e32 v67, v125
	v_mov_b32_e32 v66, v125
	v_mov_b32_e32 v65, v125
	v_mov_b32_e32 v64, v125
	v_mov_b32_e32 v63, v125
	v_mov_b32_e32 v62, v125
	v_mov_b32_e32 v61, v125
	v_mov_b32_e32 v60, v125
	v_mov_b32_e32 v59, v125
	v_mov_b32_e32 v58, v125
	v_mov_b32_e32 v49, v125
	v_mov_b32_e32 v48, v125
	v_mov_b32_e32 v47, v125
	v_mov_b32_e32 v46, v125
	v_mov_b32_e32 v45, v125
	v_mov_b32_e32 v44, v125
	v_mov_b32_e32 v43, v125
	v_mov_b32_e32 v42, v125
	v_mov_b32_e32 v33, v125
	v_mov_b32_e32 v32, v125
	v_mov_b32_e32 v31, v125
	v_mov_b32_e32 v30, v125
	v_mov_b32_e32 v29, v125
	v_mov_b32_e32 v28, v125
	v_mov_b32_e32 v27, v125
	v_mov_b32_e32 v26, v125
	v_mov_b32_e32 v17, v125
	v_mov_b32_e32 v16, v125
	v_mov_b32_e32 v15, v125
	v_mov_b32_e32 v14, v125
	v_mov_b32_e32 v13, v125
	v_mov_b32_e32 v12, v125
	v_mov_b32_e32 v11, v125
	v_mov_b32_e32 v10, v125
	v_mov_b32_e32 v57, v125
	v_mov_b32_e32 v56, v125
	v_mov_b32_e32 v55, v125
	v_mov_b32_e32 v54, v125
	v_mov_b32_e32 v53, v125
	v_mov_b32_e32 v52, v125
	v_mov_b32_e32 v51, v125
	v_mov_b32_e32 v50, v125
	v_mov_b32_e32 v41, v125
	v_mov_b32_e32 v40, v125
	v_mov_b32_e32 v39, v125
	v_mov_b32_e32 v38, v125
	v_mov_b32_e32 v37, v125
	v_mov_b32_e32 v36, v125
	v_mov_b32_e32 v35, v125
	v_mov_b32_e32 v34, v125
	v_mov_b32_e32 v25, v125
	v_mov_b32_e32 v24, v125
	v_mov_b32_e32 v23, v125
	v_mov_b32_e32 v22, v125
	v_mov_b32_e32 v21, v125
	v_mov_b32_e32 v20, v125
	v_mov_b32_e32 v19, v125
	v_mov_b32_e32 v18, v125
	v_mov_b32_e32 v9, v125
	v_mov_b32_e32 v8, v125
	v_mov_b32_e32 v7, v125
	v_mov_b32_e32 v6, v125
	v_mov_b32_e32 v5, v125
	v_mov_b32_e32 v4, v125
	v_mov_b32_e32 v3, v125
	v_mov_b32_e32 v2, v125
	s_branch .LBB0_2268
.Lmy_zr_6:
	s_and_b64 s[22:23], s[2:3], exec
	s_cselect_b32 s5, s43, s25
	s_cselect_b32 s8, s42, s24
	s_cselect_b32 s22, s39, s17
	s_cselect_b32 s23, s38, s16
	s_add_u32 s31, s16, 0x100
	s_addc_u32 s37, s17, 0
	s_add_u32 s16, s24, 0x40080
	v_mov_b32_e32 v2, 0
	s_addc_u32 s17, s25, 0
	s_mov_b32 s24, 0
	v_mov_b32_e32 v3, v2
	v_mov_b32_e32 v4, v2
	v_mov_b32_e32 v5, v2
	v_mov_b32_e32 v6, v2
	v_mov_b32_e32 v7, v2
	v_mov_b32_e32 v8, v2
	v_mov_b32_e32 v9, v2
	v_mov_b32_e32 v18, v2
	v_mov_b32_e32 v19, v2
	v_mov_b32_e32 v20, v2
	v_mov_b32_e32 v21, v2
	v_mov_b32_e32 v22, v2
	v_mov_b32_e32 v23, v2
	v_mov_b32_e32 v24, v2
	v_mov_b32_e32 v25, v2
	v_mov_b32_e32 v34, v2
	v_mov_b32_e32 v35, v2
	v_mov_b32_e32 v36, v2
	v_mov_b32_e32 v37, v2
	v_mov_b32_e32 v38, v2
	v_mov_b32_e32 v39, v2
	v_mov_b32_e32 v40, v2
	v_mov_b32_e32 v41, v2
	v_mov_b32_e32 v50, v2
	v_mov_b32_e32 v51, v2
	v_mov_b32_e32 v52, v2
	v_mov_b32_e32 v53, v2
	v_mov_b32_e32 v54, v2
	v_mov_b32_e32 v55, v2
	v_mov_b32_e32 v56, v2
	v_mov_b32_e32 v57, v2
	v_mov_b32_e32 v10, v2
	v_mov_b32_e32 v11, v2
	v_mov_b32_e32 v12, v2
	v_mov_b32_e32 v13, v2
	v_mov_b32_e32 v14, v2
	v_mov_b32_e32 v15, v2
	v_mov_b32_e32 v16, v2
	v_mov_b32_e32 v17, v2
	v_mov_b32_e32 v26, v2
	v_mov_b32_e32 v27, v2
	v_mov_b32_e32 v28, v2
	v_mov_b32_e32 v29, v2
	v_mov_b32_e32 v30, v2
	v_mov_b32_e32 v31, v2
	v_mov_b32_e32 v32, v2
	v_mov_b32_e32 v33, v2
	v_mov_b32_e32 v42, v2
	v_mov_b32_e32 v43, v2
	v_mov_b32_e32 v44, v2
	v_mov_b32_e32 v45, v2
	v_mov_b32_e32 v46, v2
	v_mov_b32_e32 v47, v2
	v_mov_b32_e32 v48, v2
	v_mov_b32_e32 v49, v2
	v_mov_b32_e32 v58, v2
	v_mov_b32_e32 v59, v2
	v_mov_b32_e32 v60, v2
	v_mov_b32_e32 v61, v2
	v_mov_b32_e32 v62, v2
	v_mov_b32_e32 v63, v2
	v_mov_b32_e32 v64, v2
	v_mov_b32_e32 v65, v2
	v_mov_b32_e32 v66, v2
	v_mov_b32_e32 v67, v2
	v_mov_b32_e32 v68, v2
	v_mov_b32_e32 v69, v2
	v_mov_b32_e32 v70, v2
	v_mov_b32_e32 v71, v2
	v_mov_b32_e32 v72, v2
	v_mov_b32_e32 v73, v2
	v_mov_b32_e32 v82, v2
	v_mov_b32_e32 v83, v2
	v_mov_b32_e32 v84, v2
	v_mov_b32_e32 v85, v2
	v_mov_b32_e32 v86, v2
	v_mov_b32_e32 v87, v2
	v_mov_b32_e32 v88, v2
	v_mov_b32_e32 v89, v2
	v_mov_b32_e32 v98, v2
	v_mov_b32_e32 v99, v2
	v_mov_b32_e32 v100, v2
	v_mov_b32_e32 v101, v2
	v_mov_b32_e32 v102, v2
	v_mov_b32_e32 v103, v2
	v_mov_b32_e32 v104, v2
	v_mov_b32_e32 v105, v2
	v_mov_b32_e32 v114, v2
	v_mov_b32_e32 v115, v2
	v_mov_b32_e32 v116, v2
	v_mov_b32_e32 v117, v2
	v_mov_b32_e32 v118, v2
	v_mov_b32_e32 v119, v2
	v_mov_b32_e32 v120, v2
	v_mov_b32_e32 v121, v2
	v_mov_b32_e32 v74, v2
	v_mov_b32_e32 v75, v2
	v_mov_b32_e32 v76, v2
	v_mov_b32_e32 v77, v2
	v_mov_b32_e32 v78, v2
	v_mov_b32_e32 v79, v2
	v_mov_b32_e32 v80, v2
	v_mov_b32_e32 v81, v2
	v_mov_b32_e32 v90, v2
	v_mov_b32_e32 v91, v2
	v_mov_b32_e32 v92, v2
	v_mov_b32_e32 v93, v2
	v_mov_b32_e32 v94, v2
	v_mov_b32_e32 v95, v2
	v_mov_b32_e32 v96, v2
	v_mov_b32_e32 v97, v2
	v_mov_b32_e32 v106, v2
	v_mov_b32_e32 v107, v2
	v_mov_b32_e32 v108, v2
	v_mov_b32_e32 v109, v2
	v_mov_b32_e32 v110, v2
	v_mov_b32_e32 v111, v2
	v_mov_b32_e32 v112, v2
	v_mov_b32_e32 v113, v2
	v_mov_b32_e32 v126, v2
	v_mov_b32_e32 v127, v2
	v_mov_b32_e32 v128, v2
	v_mov_b32_e32 v129, v2
	v_mov_b32_e32 v122, v2
	v_mov_b32_e32 v123, v2
	v_mov_b32_e32 v124, v2
	v_mov_b32_e32 v125, v2

;     __device__ __forceinline__ bool next(int i, Unit& u) const { return (i < na) ? a.next(i, u) : b.next(i - na, u); }
; template <class Epi, bool ALIGN_EPI = true, bool SP2 = true, bool QUARTER = false, class Sched = Order>
; __device__ __forceinline__ void gemm_phase(PG8_LAS unsigned char* lds, const Gemm g, const Sched& S, const Epi& E) {
;     ...
;     for (;;) {
;         const bool has_next = S.next(ui + 1, nxt);
;         const char* nA = has_next ? (const char*)(g.A + (size_t)nxt.z * g.zA) + (size_t)nxt.pm * tstepA : cA; const char* nB = has_next ? (const char*)(g.Bt + (size_t)nxt.z * g.zB) + (size_t)nxt.pn * tstepB : cB;
;         for (int t = 0; t < nt; t += 2) {
;             const bool last = (t == nt - 2);
;             const char* a1 = cA + (size_t)(t + 1) * kstep;
;             const char* a2 = last ? nA : cA + (size_t)(t + 2) * kstep; const char* b2 = last ? nB : cB + (size_t)(t + 2) * kstep;
;             const char* a3 = a2 + kstep; const char* b3 = b2 + kstep;
;     ...
; #pragma unroll
;         for (int a = 0; a < 2; ++a)
; #pragma unroll
;             for (int b = 0; b < 2; ++b)
; #pragma unroll
;                 for (int m = 0; m < 4; ++m)
; #pragma unroll
;                     for (int n = 0; n < 2; ++n) acc[a][b][m][n] = (f32x4){0.f, 0.f, 0.f, 0.f};
.LBB0_2574:
	s_ashr_i32 s47, s46, 31
	s_lshl_b64 s[6:7], s[46:47], 19
	s_add_u32 s84, s38, s6
	s_addc_u32 s85, s39, s7
	s_ashr_i32 s45, s44, 31
	s_lshl_b64 s[6:7], s[44:45], 19
	s_add_u32 s88, s55, s6
	s_addc_u32 s89, s57, s7
	v_readlane_b32 s6, v255, 19
	v_readlane_b32 s7, v255, 20
	s_andn2_b64 vcc, exec, s[6:7]
	s_cbranch_vccz .Lmy_zr_7
	v_mov_b32_e32 v129, 0
	v_mov_b32_e32 v128, v129
	v_mov_b32_e32 v127, v129
	v_mov_b32_e32 v126, v129
	v_mov_b32_e32 v121, v129
	v_mov_b32_e32 v120, v129
	v_mov_b32_e32 v119, v129
	v_mov_b32_e32 v118, v129
	v_mov_b32_e32 v113, v129
	v_mov_b32_e32 v112, v129
	v_mov_b32_e32 v111, v129
	v_mov_b32_e32 v110, v129
	v_mov_b32_e32 v105, v129
	v_mov_b32_e32 v104, v129
	v_mov_b32_e32 v103, v129
	v_mov_b32_e32 v102, v129
	v_mov_b32_e32 v97, v129
	v_mov_b32_e32 v96, v129
	v_mov_b32_e32 v95, v129
	v_mov_b32_e32 v94, v129
	v_mov_b32_e32 v89, v129
	v_mov_b32_e32 v88, v129
	v_mov_b32_e32 v87, v129
	v_mov_b32_e32 v86, v129
	v_mov_b32_e32 v81, v129
	v_mov_b32_e32 v80, v129
	v_mov_b32_e32 v79, v129
	v_mov_b32_e32 v78, v129
	v_mov_b32_e32 v73, v129
	v_mov_b32_e32 v72, v129
	v_mov_b32_e32 v71, v129
	v_mov_b32_e32 v70, v129
	v_mov_b32_e32 v125, v129
	v_mov_b32_e32 v124, v129
	v_mov_b32_e32 v123, v129
	v_mov_b32_e32 v122, v129
	v_mov_b32_e32 v117, v129
	v_mov_b32_e32 v116, v129
	v_mov_b32_e32 v115, v129
	v_mov_b32_e32 v114, v129
	v_mov_b32_e32 v109, v129
	v_mov_b32_e32 v108, v129
	v_mov_b32_e32 v107, v129
	v_mov_b32_e32 v106, v129
	v_mov_b32_e32 v101, v129
	v_mov_b32_e32 v100, v129
	v_mov_b32_e32 v99, v129
	v_mov_b32_e32 v98, v129
	v_mov_b32_e32 v93, v129
	v_mov_b32_e32 v92, v129
	v_mov_b32_e32 v91, v129
	v_mov_b32_e32 v90, v129
	v_mov_b32_e32 v85, v129
	v_mov_b32_e32 v84, v129
	v_mov_b32_e32 v83, v129
	v_mov_b32_e32 v82, v129
	v_mov_b32_e32 v77, v129
	v_mov_b32_e32 v76, v129
	v_mov_b32_e32 v75, v129
	v_mov_b32_e32 v74, v129
	v_mov_b32_e32 v69, v129
	v_mov_b32_e32 v68, v129
	v_mov_b32_e32 v67, v129
	v_mov_b32_e32 v66, v129
	v_mov_b32_e32 v65, v129
	v_mov_b32_e32 v64, v129
	v_mov_b32_e32 v63, v129
	v_mov_b32_e32 v62, v129
	v_mov_b32_e32 v57, v129
	v_mov_b32_e32 v56, v129
	v_mov_b32_e32 v55, v129
	v_mov_b32_e32 v54, v129
	v_mov_b32_e32 v49, v129
	v_mov_b32_e32 v48, v129
	v_mov_b32_e32 v47, v129
	v_mov_b32_e32 v46, v129
	v_mov_b32_e32 v41, v129
	v_mov_b32_e32 v40, v129
	v_mov_b32_e32 v39, v129
	v_mov_b32_e32 v38, v129
	v_mov_b32_e32 v33, v129
	v_mov_b32_e32 v32, v129
	v_mov_b32_e32 v31, v129
	v_mov_b32_e32 v30, v129
	v_mov_b32_e32 v25, v129
	v_mov_b32_e32 v24, v129
	v_mov_b32_e32 v23, v129
	v_mov_b32_e32 v22, v129
	v_mov_b32_e32 v17, v129
	v_mov_b32_e32 v16, v129
	v_mov_b32_e32 v15, v129
	v_mov_b32_e32 v14, v129
	v_mov_b32_e32 v9, v129
	v_mov_b32_e32 v8, v129
	v_mov_b32_e32 v7, v129
	v_mov_b32_e32 v6, v129
	v_mov_b32_e32 v61, v129
	v_mov_b32_e32 v60, v129
	v_mov_b32_e32 v59, v129
	v_mov_b32_e32 v58, v129
	v_mov_b32_e32 v53, v129
	v_mov_b32_e32 v52, v129
	v_mov_b32_e32 v51, v129
	v_mov_b32_e32 v50, v129
	v_mov_b32_e32 v45, v129
	v_mov_b32_e32 v44, v129
	v_mov_b32_e32 v43, v129
	v_mov_b32_e32 v42, v129
	v_mov_b32_e32 v37, v129
	v_mov_b32_e32 v36, v129
	v_mov_b32_e32 v35, v129
	v_mov_b32_e32 v34, v129
	v_mov_b32_e32 v29, v129
	v_mov_b32_e32 v28, v129
	v_mov_b32_e32 v27, v129
	v_mov_b32_e32 v26, v129
	v_mov_b32_e32 v21, v129
	v_mov_b32_e32 v20, v129
	v_mov_b32_e32 v19, v129
	v_mov_b32_e32 v18, v129
	v_mov_b32_e32 v13, v129
	v_mov_b32_e32 v12, v129
	v_mov_b32_e32 v11, v129
	v_mov_b32_e32 v10, v129
	v_mov_b32_e32 v5, v129
	v_mov_b32_e32 v4, v129
	v_mov_b32_e32 v3, v129
	v_mov_b32_e32 v2, v129
	s_branch .LBB0_2577
.Lmy_zr_7:
	s_and_b64 s[6:7], s[30:31], exec
	s_cselect_b32 s1, s85, s5
	s_cselect_b32 s13, s84, s4
	s_cselect_b32 s16, s89, s3
	s_cselect_b32 s17, s88, s2
	s_add_u32 s22, s2, 0x100
	s_addc_u32 s24, s3, 0
	s_add_u32 s2, s4, 0x40080
	v_mov_b32_e32 v2, 0
	s_addc_u32 s3, s5, 0
	s_mov_b32 s4, 0
	v_mov_b32_e32 v3, v2
	v_mov_b32_e32 v4, v2
	v_mov_b32_e32 v5, v2
	v_mov_b32_e32 v10, v2
	v_mov_b32_e32 v11, v2
	v_mov_b32_e32 v12, v2
	v_mov_b32_e32 v13, v2
	v_mov_b32_e32 v18, v2
	v_mov_b32_e32 v19, v2
	v_mov_b32_e32 v20, v2
	v_mov_b32_e32 v21, v2
	v_mov_b32_e32 v26, v2
	v_mov_b32_e32 v27, v2
	v_mov_b32_e32 v28, v2
	v_mov_b32_e32 v29, v2
	v_mov_b32_e32 v34, v2
	v_mov_b32_e32 v35, v2
	v_mov_b32_e32 v36, v2
	v_mov_b32_e32 v37, v2
	v_mov_b32_e32 v42, v2
	v_mov_b32_e32 v43, v2
	v_mov_b32_e32 v44, v2
	v_mov_b32_e32 v45, v2
	v_mov_b32_e32 v50, v2
	v_mov_b32_e32 v51, v2
	v_mov_b32_e32 v52, v2
	v_mov_b32_e32 v53, v2
	v_mov_b32_e32 v58, v2
	v_mov_b32_e32 v59, v2
	v_mov_b32_e32 v60, v2
	v_mov_b32_e32 v61, v2
	v_mov_b32_e32 v6, v2
	v_mov_b32_e32 v7, v2
	v_mov_b32_e32 v8, v2
	v_mov_b32_e32 v9, v2
	v_mov_b32_e32 v14, v2
	v_mov_b32_e32 v15, v2
	v_mov_b32_e32 v16, v2
	v_mov_b32_e32 v17, v2
	v_mov_b32_e32 v22, v2
	v_mov_b32_e32 v23, v2
	v_mov_b32_e32 v24, v2
	v_mov_b32_e32 v25, v2
	v_mov_b32_e32 v30, v2
	v_mov_b32_e32 v31, v2
	v_mov_b32_e32 v32, v2
	v_mov_b32_e32 v33, v2
	v_mov_b32_e32 v38, v2
	v_mov_b32_e32 v39, v2
	v_mov_b32_e32 v40, v2
	v_mov_b32_e32 v41, v2
	v_mov_b32_e32 v46, v2
	v_mov_b32_e32 v47, v2
	v_mov_b32_e32 v48, v2
	v_mov_b32_e32 v49, v2
	v_mov_b32_e32 v54, v2
	v_mov_b32_e32 v55, v2
	v_mov_b32_e32 v56, v2
	v_mov_b32_e32 v57, v2
	v_mov_b32_e32 v62, v2
	v_mov_b32_e32 v63, v2
	v_mov_b32_e32 v64, v2
	v_mov_b32_e32 v65, v2
	v_mov_b32_e32 v66, v2
	v_mov_b32_e32 v67, v2
	v_mov_b32_e32 v68, v2
	v_mov_b32_e32 v69, v2
	v_mov_b32_e32 v74, v2
	v_mov_b32_e32 v75, v2
	v_mov_b32_e32 v76, v2
	v_mov_b32_e32 v77, v2
	v_mov_b32_e32 v82, v2
	v_mov_b32_e32 v83, v2
	v_mov_b32_e32 v84, v2
	v_mov_b32_e32 v85, v2
	v_mov_b32_e32 v90, v2
	v_mov_b32_e32 v91, v2
	v_mov_b32_e32 v92, v2
	v_mov_b32_e32 v93, v2
	v_mov_b32_e32 v98, v2
	v_mov_b32_e32 v99, v2
	v_mov_b32_e32 v100, v2
	v_mov_b32_e32 v101, v2
	v_mov_b32_e32 v106, v2
	v_mov_b32_e32 v107, v2
	v_mov_b32_e32 v108, v2
	v_mov_b32_e32 v109, v2
	v_mov_b32_e32 v114, v2
	v_mov_b32_e32 v115, v2
	v_mov_b32_e32 v116, v2
	v_mov_b32_e32 v117, v2
	v_mov_b32_e32 v122, v2
	v_mov_b32_e32 v123, v2
	v_mov_b32_e32 v124, v2
	v_mov_b32_e32 v125, v2
	v_mov_b32_e32 v70, v2
	v_mov_b32_e32 v71, v2
	v_mov_b32_e32 v72, v2
	v_mov_b32_e32 v73, v2
	v_mov_b32_e32 v78, v2
	v_mov_b32_e32 v79, v2
	v_mov_b32_e32 v80, v2
	v_mov_b32_e32 v81, v2
	v_mov_b32_e32 v86, v2
	v_mov_b32_e32 v87, v2
	v_mov_b32_e32 v88, v2
	v_mov_b32_e32 v89, v2
	v_mov_b32_e32 v94, v2
	v_mov_b32_e32 v95, v2
	v_mov_b32_e32 v96, v2
	v_mov_b32_e32 v97, v2
	v_mov_b32_e32 v102, v2
	v_mov_b32_e32 v103, v2
	v_mov_b32_e32 v104, v2
	v_mov_b32_e32 v105, v2
	v_mov_b32_e32 v110, v2
	v_mov_b32_e32 v111, v2
	v_mov_b32_e32 v112, v2
	v_mov_b32_e32 v113, v2
	v_mov_b32_e32 v118, v2
	v_mov_b32_e32 v119, v2
	v_mov_b32_e32 v120, v2
	v_mov_b32_e32 v121, v2
	v_mov_b32_e32 v126, v2
	v_mov_b32_e32 v127, v2
	v_mov_b32_e32 v128, v2
	v_mov_b32_e32 v129, v2

;     __device__ __forceinline__ bool next(int i, Unit& u) const { return (i < na) ? a.next(i, u) : b.next(i - na, u); }
; template <class Epi, bool ALIGN_EPI = true, bool SP2 = true, bool QUARTER = false, class Sched = Order>
; __device__ __forceinline__ void gemm_phase(PG8_LAS unsigned char* lds, const Gemm g, const Sched& S, const Epi& E) {
;     ...
;     for (;;) {
;         const bool has_next = S.next(ui + 1, nxt);
;         const char* nA = has_next ? (const char*)(g.A + (size_t)nxt.z * g.zA) + (size_t)nxt.pm * tstepA : cA; const char* nB = has_next ? (const char*)(g.Bt + (size_t)nxt.z * g.zB) + (size_t)nxt.pn * tstepB : cB;
;         for (int t = 0; t < nt; t += 2) {
;             const bool last = (t == nt - 2);
;             const char* a1 = cA + (size_t)(t + 1) * kstep;
;             const char* a2 = last ? nA : cA + (size_t)(t + 2) * kstep; const char* b2 = last ? nB : cB + (size_t)(t + 2) * kstep;
;             const char* a3 = a2 + kstep; const char* b3 = b2 + kstep;
;     ...
; #pragma unroll
;         for (int a = 0; a < 2; ++a)
; #pragma unroll
;             for (int b = 0; b < 2; ++b)
; #pragma unroll
;                 for (int m = 0; m < 4; ++m)
; #pragma unroll
;                     for (int n = 0; n < 2; ++n) acc[a][b][m][n] = (f32x4){0.f, 0.f, 0.f, 0.f};
.LBB0_2716:
	s_ashr_i32 s31, s30, 31
	s_lshl_b64 s[36:37], s[30:31], 17
	s_add_u32 s36, s54, s36
	s_addc_u32 s37, s55, s37
	s_ashr_i32 s29, s28, 31
	s_lshl_b64 s[42:43], s[28:29], 17
	s_add_u32 s42, s56, s42
	s_addc_u32 s43, s57, s43
	s_andn2_b64 vcc, exec, s[6:7]
	s_cbranch_vccz .Lmy_zr_8
	v_mov_b32_e32 v125, 0
	v_mov_b32_e32 v124, v125
	v_mov_b32_e32 v123, v125
	v_mov_b32_e32 v122, v125
	v_mov_b32_e32 v129, v125
	v_mov_b32_e32 v128, v125
	v_mov_b32_e32 v127, v125
	v_mov_b32_e32 v126, v125
	v_mov_b32_e32 v113, v125
	v_mov_b32_e32 v112, v125
	v_mov_b32_e32 v111, v125
	v_mov_b32_e32 v110, v125
	v_mov_b32_e32 v109, v125
	v_mov_b32_e32 v108, v125
	v_mov_b32_e32 v107, v125
	v_mov_b32_e32 v106, v125
	v_mov_b32_e32 v97, v125
	v_mov_b32_e32 v96, v125
	v_mov_b32_e32 v95, v125
	v_mov_b32_e32 v94, v125
	v_mov_b32_e32 v93, v125
	v_mov_b32_e32 v92, v125
	v_mov_b32_e32 v91, v125
	v_mov_b32_e32 v90, v125
	v_mov_b32_e32 v81, v125
	v_mov_b32_e32 v80, v125
	v_mov_b32_e32 v79, v125
	v_mov_b32_e32 v78, v125
	v_mov_b32_e32 v77, v125
	v_mov_b32_e32 v76, v125
	v_mov_b32_e32 v75, v125
	v_mov_b32_e32 v74, v125
	v_mov_b32_e32 v121, v125
	v_mov_b32_e32 v120, v125
	v_mov_b32_e32 v119, v125
	v_mov_b32_e32 v118, v125
	v_mov_b32_e32 v117, v125
	v_mov_b32_e32 v116, v125
	v_mov_b32_e32 v115, v125
	v_mov_b32_e32 v114, v125
	v_mov_b32_e32 v105, v125
	v_mov_b32_e32 v104, v125
	v_mov_b32_e32 v103, v125
	v_mov_b32_e32 v102, v125
	v_mov_b32_e32 v101, v125
	v_mov_b32_e32 v100, v125
	v_mov_b32_e32 v99, v125
	v_mov_b32_e32 v98, v125
	v_mov_b32_e32 v89, v125
	v_mov_b32_e32 v88, v125
	v_mov_b32_e32 v87, v125
	v_mov_b32_e32 v86, v125
	v_mov_b32_e32 v85, v125
	v_mov_b32_e32 v84, v125
	v_mov_b32_e32 v83, v125
	v_mov_b32_e32 v82, v125
	v_mov_b32_e32 v73, v125
	v_mov_b32_e32 v72, v125
	v_mov_b32_e32 v71, v125
	v_mov_b32_e32 v70, v125
	v_mov_b32_e32 v69, v125
	v_mov_b32_e32 v68, v125
	v_mov_b32_e32 v67, v125
	v_mov_b32_e32 v66, v125
	v_mov_b32_e32 v65, v125
	v_mov_b32_e32 v64, v125
	v_mov_b32_e32 v63, v125
	v_mov_b32_e32 v62, v125
	v_mov_b32_e32 v61, v125
	v_mov_b32_e32 v60, v125
	v_mov_b32_e32 v59, v125
	v_mov_b32_e32 v58, v125
	v_mov_b32_e32 v49, v125
	v_mov_b32_e32 v48, v125
	v_mov_b32_e32 v47, v125
	v_mov_b32_e32 v46, v125
	v_mov_b32_e32 v45, v125
	v_mov_b32_e32 v44, v125
	v_mov_b32_e32 v43, v125
	v_mov_b32_e32 v42, v125
	v_mov_b32_e32 v33, v125
	v_mov_b32_e32 v32, v125
	v_mov_b32_e32 v31, v125
	v_mov_b32_e32 v30, v125
	v_mov_b32_e32 v29, v125
	v_mov_b32_e32 v28, v125
	v_mov_b32_e32 v27, v125
	v_mov_b32_e32 v26, v125
	v_mov_b32_e32 v17, v125
	v_mov_b32_e32 v16, v125
	v_mov_b32_e32 v15, v125
	v_mov_b32_e32 v14, v125
	v_mov_b32_e32 v13, v125
	v_mov_b32_e32 v12, v125
	v_mov_b32_e32 v11, v125
	v_mov_b32_e32 v10, v125
	v_mov_b32_e32 v57, v125
	v_mov_b32_e32 v56, v125
	v_mov_b32_e32 v55, v125
	v_mov_b32_e32 v54, v125
	v_mov_b32_e32 v53, v125
	v_mov_b32_e32 v52, v125
	v_mov_b32_e32 v51, v125
	v_mov_b32_e32 v50, v125
	v_mov_b32_e32 v41, v125
	v_mov_b32_e32 v40, v125
	v_mov_b32_e32 v39, v125
	v_mov_b32_e32 v38, v125
	v_mov_b32_e32 v37, v125
	v_mov_b32_e32 v36, v125
	v_mov_b32_e32 v35, v125
	v_mov_b32_e32 v34, v125
	v_mov_b32_e32 v25, v125
	v_mov_b32_e32 v24, v125
	v_mov_b32_e32 v23, v125
	v_mov_b32_e32 v22, v125
	v_mov_b32_e32 v21, v125
	v_mov_b32_e32 v20, v125
	v_mov_b32_e32 v19, v125
	v_mov_b32_e32 v18, v125
	v_mov_b32_e32 v9, v125
	v_mov_b32_e32 v8, v125
	v_mov_b32_e32 v7, v125
	v_mov_b32_e32 v6, v125
	v_mov_b32_e32 v5, v125
	v_mov_b32_e32 v4, v125
	v_mov_b32_e32 v3, v125
	v_mov_b32_e32 v2, v125
	s_branch .LBB0_2719
.Lmy_zr_8:
	s_and_b64 s[48:49], s[2:3], exec
	s_cselect_b32 s22, s37, s47
	s_cselect_b32 s29, s36, s46
	s_cselect_b32 s31, s43, s45
	s_cselect_b32 s73, s42, s44
	s_add_u32 s74, s44, 0x100
	s_addc_u32 s75, s45, 0
	s_add_u32 s44, s46, 0x10080
	v_mov_b32_e32 v2, 0
	s_addc_u32 s45, s47, 0
	s_mov_b32 s46, 0
	v_mov_b32_e32 v3, v2
	v_mov_b32_e32 v4, v2
	v_mov_b32_e32 v5, v2
	v_mov_b32_e32 v6, v2
	v_mov_b32_e32 v7, v2
	v_mov_b32_e32 v8, v2
	v_mov_b32_e32 v9, v2
	v_mov_b32_e32 v18, v2
	v_mov_b32_e32 v19, v2
	v_mov_b32_e32 v20, v2
	v_mov_b32_e32 v21, v2
	v_mov_b32_e32 v22, v2
	v_mov_b32_e32 v23, v2
	v_mov_b32_e32 v24, v2
	v_mov_b32_e32 v25, v2
	v_mov_b32_e32 v34, v2
	v_mov_b32_e32 v35, v2
	v_mov_b32_e32 v36, v2
	v_mov_b32_e32 v37, v2
	v_mov_b32_e32 v38, v2
	v_mov_b32_e32 v39, v2
	v_mov_b32_e32 v40, v2
	v_mov_b32_e32 v41, v2
	v_mov_b32_e32 v50, v2
	v_mov_b32_e32 v51, v2
	v_mov_b32_e32 v52, v2
	v_mov_b32_e32 v53, v2
	v_mov_b32_e32 v54, v2
	v_mov_b32_e32 v55, v2
	v_mov_b32_e32 v56, v2
	v_mov_b32_e32 v57, v2
	v_mov_b32_e32 v10, v2
	v_mov_b32_e32 v11, v2
	v_mov_b32_e32 v12, v2
	v_mov_b32_e32 v13, v2
	v_mov_b32_e32 v14, v2
	v_mov_b32_e32 v15, v2
	v_mov_b32_e32 v16, v2
	v_mov_b32_e32 v17, v2
	v_mov_b32_e32 v26, v2
	v_mov_b32_e32 v27, v2
	v_mov_b32_e32 v28, v2
	v_mov_b32_e32 v29, v2
	v_mov_b32_e32 v30, v2
	v_mov_b32_e32 v31, v2
	v_mov_b32_e32 v32, v2
	v_mov_b32_e32 v33, v2
	v_mov_b32_e32 v42, v2
	v_mov_b32_e32 v43, v2
	v_mov_b32_e32 v44, v2
	v_mov_b32_e32 v45, v2
	v_mov_b32_e32 v46, v2
	v_mov_b32_e32 v47, v2
	v_mov_b32_e32 v48, v2
	v_mov_b32_e32 v49, v2
	v_mov_b32_e32 v58, v2
	v_mov_b32_e32 v59, v2
	v_mov_b32_e32 v60, v2
	v_mov_b32_e32 v61, v2
	v_mov_b32_e32 v62, v2
	v_mov_b32_e32 v63, v2
	v_mov_b32_e32 v64, v2
	v_mov_b32_e32 v65, v2
	v_mov_b32_e32 v66, v2
	v_mov_b32_e32 v67, v2
	v_mov_b32_e32 v68, v2
	v_mov_b32_e32 v69, v2
	v_mov_b32_e32 v70, v2
	v_mov_b32_e32 v71, v2
	v_mov_b32_e32 v72, v2
	v_mov_b32_e32 v73, v2
	v_mov_b32_e32 v82, v2
	v_mov_b32_e32 v83, v2
	v_mov_b32_e32 v84, v2
	v_mov_b32_e32 v85, v2
	v_mov_b32_e32 v86, v2
	v_mov_b32_e32 v87, v2
	v_mov_b32_e32 v88, v2
	v_mov_b32_e32 v89, v2
	v_mov_b32_e32 v98, v2
	v_mov_b32_e32 v99, v2
	v_mov_b32_e32 v100, v2
	v_mov_b32_e32 v101, v2
	v_mov_b32_e32 v102, v2
	v_mov_b32_e32 v103, v2
	v_mov_b32_e32 v104, v2
	v_mov_b32_e32 v105, v2
	v_mov_b32_e32 v114, v2
	v_mov_b32_e32 v115, v2
	v_mov_b32_e32 v116, v2
	v_mov_b32_e32 v117, v2
	v_mov_b32_e32 v118, v2
	v_mov_b32_e32 v119, v2
	v_mov_b32_e32 v120, v2
	v_mov_b32_e32 v121, v2
	v_mov_b32_e32 v74, v2
	v_mov_b32_e32 v75, v2
	v_mov_b32_e32 v76, v2
	v_mov_b32_e32 v77, v2
	v_mov_b32_e32 v78, v2
	v_mov_b32_e32 v79, v2
	v_mov_b32_e32 v80, v2
	v_mov_b32_e32 v81, v2
	v_mov_b32_e32 v90, v2
	v_mov_b32_e32 v91, v2
	v_mov_b32_e32 v92, v2
	v_mov_b32_e32 v93, v2
	v_mov_b32_e32 v94, v2
	v_mov_b32_e32 v95, v2
	v_mov_b32_e32 v96, v2
	v_mov_b32_e32 v97, v2
	v_mov_b32_e32 v106, v2
	v_mov_b32_e32 v107, v2
	v_mov_b32_e32 v108, v2
	v_mov_b32_e32 v109, v2
	v_mov_b32_e32 v110, v2
	v_mov_b32_e32 v111, v2
	v_mov_b32_e32 v112, v2
	v_mov_b32_e32 v113, v2
	v_mov_b32_e32 v126, v2
	v_mov_b32_e32 v127, v2
	v_mov_b32_e32 v128, v2
	v_mov_b32_e32 v129, v2
	v_mov_b32_e32 v122, v2
	v_mov_b32_e32 v123, v2
	v_mov_b32_e32 v124, v2
	v_mov_b32_e32 v125, v2

;     __device__ __forceinline__ bool next(int i, Unit& u) const { return (i < na) ? a.next(i, u) : b.next(i - na, u); }
; template <class Epi, bool ALIGN_EPI = true, bool SP2 = true, bool QUARTER = false, class Sched = Order>
; __device__ __forceinline__ void gemm_phase(PG8_LAS unsigned char* lds, const Gemm g, const Sched& S, const Epi& E) {
;     ...
;     for (;;) {
;         const bool has_next = S.next(ui + 1, nxt);
;         const char* nA = has_next ? (const char*)(g.A + (size_t)nxt.z * g.zA) + (size_t)nxt.pm * tstepA : cA; const char* nB = has_next ? (const char*)(g.Bt + (size_t)nxt.z * g.zB) + (size_t)nxt.pn * tstepB : cB;
;         for (int t = 0; t < nt; t += 2) {
;             const bool last = (t == nt - 2);
;             const char* a1 = cA + (size_t)(t + 1) * kstep;
;             const char* a2 = last ? nA : cA + (size_t)(t + 2) * kstep; const char* b2 = last ? nB : cB + (size_t)(t + 2) * kstep;
;             const char* a3 = a2 + kstep; const char* b3 = b2 + kstep;
;     ...
; #pragma unroll
;         for (int a = 0; a < 2; ++a)
; #pragma unroll
;             for (int b = 0; b < 2; ++b)
; #pragma unroll
;                 for (int m = 0; m < 4; ++m)
; #pragma unroll
;                     for (int n = 0; n < 2; ++n) acc[a][b][m][n] = (f32x4){0.f, 0.f, 0.f, 0.f};
.LBB0_2983:
	s_andn2_b64 vcc, exec, s[12:13]
	s_cbranch_vccz .Lmy_zr_9
	v_mov_b32_e32 v129, 0
	v_mov_b32_e32 v128, v129
	v_mov_b32_e32 v127, v129
	v_mov_b32_e32 v126, v129
	v_mov_b32_e32 v125, v129
	v_mov_b32_e32 v124, v129
	v_mov_b32_e32 v123, v129
	v_mov_b32_e32 v122, v129
	v_mov_b32_e32 v113, v129
	v_mov_b32_e32 v112, v129
	v_mov_b32_e32 v111, v129
	v_mov_b32_e32 v110, v129
	v_mov_b32_e32 v109, v129
	v_mov_b32_e32 v108, v129
	v_mov_b32_e32 v107, v129
	v_mov_b32_e32 v106, v129
	v_mov_b32_e32 v97, v129
	v_mov_b32_e32 v96, v129
	v_mov_b32_e32 v95, v129
	v_mov_b32_e32 v94, v129
	v_mov_b32_e32 v93, v129
	v_mov_b32_e32 v92, v129
	v_mov_b32_e32 v91, v129
	v_mov_b32_e32 v90, v129
	v_mov_b32_e32 v81, v129
	v_mov_b32_e32 v80, v129
	v_mov_b32_e32 v79, v129
	v_mov_b32_e32 v78, v129
	v_mov_b32_e32 v77, v129
	v_mov_b32_e32 v76, v129
	v_mov_b32_e32 v75, v129
	v_mov_b32_e32 v74, v129
	v_mov_b32_e32 v121, v129
	v_mov_b32_e32 v120, v129
	v_mov_b32_e32 v119, v129
	v_mov_b32_e32 v118, v129
	v_mov_b32_e32 v117, v129
	v_mov_b32_e32 v116, v129
	v_mov_b32_e32 v115, v129
	v_mov_b32_e32 v114, v129
	v_mov_b32_e32 v105, v129
	v_mov_b32_e32 v104, v129
	v_mov_b32_e32 v103, v129
	v_mov_b32_e32 v102, v129
	v_mov_b32_e32 v101, v129
	v_mov_b32_e32 v100, v129
	v_mov_b32_e32 v99, v129
	v_mov_b32_e32 v98, v129
	v_mov_b32_e32 v89, v129
	v_mov_b32_e32 v88, v129
	v_mov_b32_e32 v87, v129
	v_mov_b32_e32 v86, v129
	v_mov_b32_e32 v85, v129
	v_mov_b32_e32 v84, v129
	v_mov_b32_e32 v83, v129
	v_mov_b32_e32 v82, v129
	v_mov_b32_e32 v73, v129
	v_mov_b32_e32 v72, v129
	v_mov_b32_e32 v71, v129
	v_mov_b32_e32 v70, v129
	v_mov_b32_e32 v69, v129
	v_mov_b32_e32 v68, v129
	v_mov_b32_e32 v67, v129
	v_mov_b32_e32 v66, v129
	v_mov_b32_e32 v65, v129
	v_mov_b32_e32 v64, v129
	v_mov_b32_e32 v63, v129
	v_mov_b32_e32 v62, v129
	v_mov_b32_e32 v61, v129
	v_mov_b32_e32 v60, v129
	v_mov_b32_e32 v59, v129
	v_mov_b32_e32 v58, v129
	v_mov_b32_e32 v49, v129
	v_mov_b32_e32 v48, v129
	v_mov_b32_e32 v47, v129
	v_mov_b32_e32 v46, v129
	v_mov_b32_e32 v45, v129
	v_mov_b32_e32 v44, v129
	v_mov_b32_e32 v43, v129
	v_mov_b32_e32 v42, v129
	v_mov_b32_e32 v33, v129
	v_mov_b32_e32 v32, v129
	v_mov_b32_e32 v31, v129
	v_mov_b32_e32 v30, v129
	v_mov_b32_e32 v29, v129
	v_mov_b32_e32 v28, v129
	v_mov_b32_e32 v27, v129
	v_mov_b32_e32 v26, v129
	v_mov_b32_e32 v17, v129
	v_mov_b32_e32 v16, v129
	v_mov_b32_e32 v15, v129
	v_mov_b32_e32 v14, v129
	v_mov_b32_e32 v13, v129
	v_mov_b32_e32 v12, v129
	v_mov_b32_e32 v11, v129
	v_mov_b32_e32 v10, v129
	v_mov_b32_e32 v57, v129
	v_mov_b32_e32 v56, v129
	v_mov_b32_e32 v55, v129
	v_mov_b32_e32 v54, v129
	v_mov_b32_e32 v53, v129
	v_mov_b32_e32 v52, v129
	v_mov_b32_e32 v51, v129
	v_mov_b32_e32 v50, v129
	v_mov_b32_e32 v41, v129
	v_mov_b32_e32 v40, v129
	v_mov_b32_e32 v39, v129
	v_mov_b32_e32 v38, v129
	v_mov_b32_e32 v37, v129
	v_mov_b32_e32 v36, v129
	v_mov_b32_e32 v35, v129
	v_mov_b32_e32 v34, v129
	v_mov_b32_e32 v25, v129
	v_mov_b32_e32 v24, v129
	v_mov_b32_e32 v23, v129
	v_mov_b32_e32 v22, v129
	v_mov_b32_e32 v21, v129
	v_mov_b32_e32 v20, v129
	v_mov_b32_e32 v19, v129
	v_mov_b32_e32 v18, v129
	v_mov_b32_e32 v9, v129
	v_mov_b32_e32 v8, v129
	v_mov_b32_e32 v7, v129
	v_mov_b32_e32 v6, v129
	v_mov_b32_e32 v5, v129
	v_mov_b32_e32 v4, v129
	v_mov_b32_e32 v3, v129
	v_mov_b32_e32 v2, v129
	s_branch .LBB0_2986
.Lmy_zr_9:
	s_add_u32 s0, s24, 0x100
	v_mov_b32_e32 v2, 0
	s_addc_u32 s22, s25, 0
	s_mov_b32 s26, 0
	v_mov_b32_e32 v3, v2
	v_mov_b32_e32 v4, v2
	v_mov_b32_e32 v5, v2
	v_mov_b32_e32 v6, v2
	v_mov_b32_e32 v7, v2
	v_mov_b32_e32 v8, v2
	v_mov_b32_e32 v9, v2
	v_mov_b32_e32 v18, v2
	v_mov_b32_e32 v19, v2
	v_mov_b32_e32 v20, v2
	v_mov_b32_e32 v21, v2
	v_mov_b32_e32 v22, v2
	v_mov_b32_e32 v23, v2
	v_mov_b32_e32 v24, v2
	v_mov_b32_e32 v25, v2
	v_mov_b32_e32 v34, v2
	v_mov_b32_e32 v35, v2
	v_mov_b32_e32 v36, v2
	v_mov_b32_e32 v37, v2
	v_mov_b32_e32 v38, v2
	v_mov_b32_e32 v39, v2
	v_mov_b32_e32 v40, v2
	v_mov_b32_e32 v41, v2
	v_mov_b32_e32 v50, v2
	v_mov_b32_e32 v51, v2
	v_mov_b32_e32 v52, v2
	v_mov_b32_e32 v53, v2
	v_mov_b32_e32 v54, v2
	v_mov_b32_e32 v55, v2
	v_mov_b32_e32 v56, v2
	v_mov_b32_e32 v57, v2
	v_mov_b32_e32 v10, v2
	v_mov_b32_e32 v11, v2
	v_mov_b32_e32 v12, v2
	v_mov_b32_e32 v13, v2
	v_mov_b32_e32 v14, v2
	v_mov_b32_e32 v15, v2
	v_mov_b32_e32 v16, v2
	v_mov_b32_e32 v17, v2
	v_mov_b32_e32 v26, v2
	v_mov_b32_e32 v27, v2
	v_mov_b32_e32 v28, v2
	v_mov_b32_e32 v29, v2
	v_mov_b32_e32 v30, v2
	v_mov_b32_e32 v31, v2
	v_mov_b32_e32 v32, v2
	v_mov_b32_e32 v33, v2
	v_mov_b32_e32 v42, v2
	v_mov_b32_e32 v43, v2
	v_mov_b32_e32 v44, v2
	v_mov_b32_e32 v45, v2
	v_mov_b32_e32 v46, v2
	v_mov_b32_e32 v47, v2
	v_mov_b32_e32 v48, v2
	v_mov_b32_e32 v49, v2
	v_mov_b32_e32 v58, v2
	v_mov_b32_e32 v59, v2
	v_mov_b32_e32 v60, v2
	v_mov_b32_e32 v61, v2
	v_mov_b32_e32 v62, v2
	v_mov_b32_e32 v63, v2
	v_mov_b32_e32 v64, v2
	v_mov_b32_e32 v65, v2
	v_mov_b32_e32 v66, v2
	v_mov_b32_e32 v67, v2
	v_mov_b32_e32 v68, v2
	v_mov_b32_e32 v69, v2
	v_mov_b32_e32 v70, v2
	v_mov_b32_e32 v71, v2
	v_mov_b32_e32 v72, v2
	v_mov_b32_e32 v73, v2
	v_mov_b32_e32 v82, v2
	v_mov_b32_e32 v83, v2
	v_mov_b32_e32 v84, v2
	v_mov_b32_e32 v85, v2
	v_mov_b32_e32 v86, v2
	v_mov_b32_e32 v87, v2
	v_mov_b32_e32 v88, v2
	v_mov_b32_e32 v89, v2
	v_mov_b32_e32 v98, v2
	v_mov_b32_e32 v99, v2
	v_mov_b32_e32 v100, v2
	v_mov_b32_e32 v101, v2
	v_mov_b32_e32 v102, v2
	v_mov_b32_e32 v103, v2
	v_mov_b32_e32 v104, v2
	v_mov_b32_e32 v105, v2
	v_mov_b32_e32 v114, v2
	v_mov_b32_e32 v115, v2
	v_mov_b32_e32 v116, v2
	v_mov_b32_e32 v117, v2
	v_mov_b32_e32 v118, v2
	v_mov_b32_e32 v119, v2
	v_mov_b32_e32 v120, v2
	v_mov_b32_e32 v121, v2
	v_mov_b32_e32 v74, v2
	v_mov_b32_e32 v75, v2
	v_mov_b32_e32 v76, v2
	v_mov_b32_e32 v77, v2
	v_mov_b32_e32 v78, v2
	v_mov_b32_e32 v79, v2
	v_mov_b32_e32 v80, v2
	v_mov_b32_e32 v81, v2
	v_mov_b32_e32 v90, v2
	v_mov_b32_e32 v91, v2
	v_mov_b32_e32 v92, v2
	v_mov_b32_e32 v93, v2
	v_mov_b32_e32 v94, v2
	v_mov_b32_e32 v95, v2
	v_mov_b32_e32 v96, v2
	v_mov_b32_e32 v97, v2
	v_mov_b32_e32 v106, v2
	v_mov_b32_e32 v107, v2
	v_mov_b32_e32 v108, v2
	v_mov_b32_e32 v109, v2
	v_mov_b32_e32 v110, v2
	v_mov_b32_e32 v111, v2
	v_mov_b32_e32 v112, v2
	v_mov_b32_e32 v113, v2
	v_mov_b32_e32 v122, v2
	v_mov_b32_e32 v123, v2
	v_mov_b32_e32 v124, v2
	v_mov_b32_e32 v125, v2
	v_mov_b32_e32 v126, v2
	v_mov_b32_e32 v127, v2
	v_mov_b32_e32 v128, v2
	v_mov_b32_e32 v129, v2

; template <class Epi, bool ALIGN_EPI = true, bool SP2 = true, bool QUARTER = false, class Sched = Order>
; __device__ __forceinline__ void gemm_phase(PG8_LAS unsigned char* lds, const Gemm g, const Sched& S, const Epi& E) {
;     ...
; #pragma unroll
;         for (int a = 0; a < 2; ++a)
; #pragma unroll
;             for (int b = 0; b < 2; ++b)
; #pragma unroll
;                 for (int m = 0; m < 4; ++m)
; #pragma unroll
;                     for (int n = 0; n < 2; ++n) acc[a][b][m][n] = (f32x4){0.f, 0.f, 0.f, 0.f};
.LBB0_3191:
	s_andn2_b64 vcc, exec, s[10:11]
	s_cbranch_vccz .Lmy_zr_10
	v_mov_b32_e32 v129, 0
	v_mov_b32_e32 v128, v129
	v_mov_b32_e32 v127, v129
	v_mov_b32_e32 v126, v129
	v_mov_b32_e32 v125, v129
	v_mov_b32_e32 v124, v129
	v_mov_b32_e32 v123, v129
	v_mov_b32_e32 v122, v129
	v_mov_b32_e32 v113, v129
	v_mov_b32_e32 v112, v129
	v_mov_b32_e32 v111, v129
	v_mov_b32_e32 v110, v129
	v_mov_b32_e32 v109, v129
	v_mov_b32_e32 v108, v129
	v_mov_b32_e32 v107, v129
	v_mov_b32_e32 v106, v129
	v_mov_b32_e32 v97, v129
	v_mov_b32_e32 v96, v129
	v_mov_b32_e32 v95, v129
	v_mov_b32_e32 v94, v129
	v_mov_b32_e32 v93, v129
	v_mov_b32_e32 v92, v129
	v_mov_b32_e32 v91, v129
	v_mov_b32_e32 v90, v129
	v_mov_b32_e32 v81, v129
	v_mov_b32_e32 v80, v129
	v_mov_b32_e32 v79, v129
	v_mov_b32_e32 v78, v129
	v_mov_b32_e32 v77, v129
	v_mov_b32_e32 v76, v129
	v_mov_b32_e32 v75, v129
	v_mov_b32_e32 v74, v129
	v_mov_b32_e32 v121, v129
	v_mov_b32_e32 v120, v129
	v_mov_b32_e32 v119, v129
	v_mov_b32_e32 v118, v129
	v_mov_b32_e32 v117, v129
	v_mov_b32_e32 v116, v129
	v_mov_b32_e32 v115, v129
	v_mov_b32_e32 v114, v129
	v_mov_b32_e32 v105, v129
	v_mov_b32_e32 v104, v129
	v_mov_b32_e32 v103, v129
	v_mov_b32_e32 v102, v129
	v_mov_b32_e32 v101, v129
	v_mov_b32_e32 v100, v129
	v_mov_b32_e32 v99, v129
	v_mov_b32_e32 v98, v129
	v_mov_b32_e32 v89, v129
	v_mov_b32_e32 v88, v129
	v_mov_b32_e32 v87, v129
	v_mov_b32_e32 v86, v129
	v_mov_b32_e32 v85, v129
	v_mov_b32_e32 v84, v129
	v_mov_b32_e32 v83, v129
	v_mov_b32_e32 v82, v129
	v_mov_b32_e32 v73, v129
	v_mov_b32_e32 v72, v129
	v_mov_b32_e32 v71, v129
	v_mov_b32_e32 v70, v129
	v_mov_b32_e32 v69, v129
	v_mov_b32_e32 v68, v129
	v_mov_b32_e32 v67, v129
	v_mov_b32_e32 v66, v129
	v_mov_b32_e32 v65, v129
	v_mov_b32_e32 v64, v129
	v_mov_b32_e32 v63, v129
	v_mov_b32_e32 v62, v129
	v_mov_b32_e32 v61, v129
	v_mov_b32_e32 v60, v129
	v_mov_b32_e32 v59, v129
	v_mov_b32_e32 v58, v129
	v_mov_b32_e32 v49, v129
	v_mov_b32_e32 v48, v129
	v_mov_b32_e32 v47, v129
	v_mov_b32_e32 v46, v129
	v_mov_b32_e32 v45, v129
	v_mov_b32_e32 v44, v129
	v_mov_b32_e32 v43, v129
	v_mov_b32_e32 v42, v129
	v_mov_b32_e32 v33, v129
	v_mov_b32_e32 v32, v129
	v_mov_b32_e32 v31, v129
	v_mov_b32_e32 v30, v129
	v_mov_b32_e32 v29, v129
	v_mov_b32_e32 v28, v129
	v_mov_b32_e32 v27, v129
	v_mov_b32_e32 v26, v129
	v_mov_b32_e32 v17, v129
	v_mov_b32_e32 v16, v129
	v_mov_b32_e32 v15, v129
	v_mov_b32_e32 v14, v129
	v_mov_b32_e32 v13, v129
	v_mov_b32_e32 v12, v129
	v_mov_b32_e32 v11, v129
	v_mov_b32_e32 v10, v129
	v_mov_b32_e32 v57, v129
	v_mov_b32_e32 v56, v129
	v_mov_b32_e32 v55, v129
	v_mov_b32_e32 v54, v129
	v_mov_b32_e32 v53, v129
	v_mov_b32_e32 v52, v129
	v_mov_b32_e32 v51, v129
	v_mov_b32_e32 v50, v129
	v_mov_b32_e32 v41, v129
	v_mov_b32_e32 v40, v129
	v_mov_b32_e32 v39, v129
	v_mov_b32_e32 v38, v129
	v_mov_b32_e32 v37, v129
	v_mov_b32_e32 v36, v129
	v_mov_b32_e32 v35, v129
	v_mov_b32_e32 v34, v129
	v_mov_b32_e32 v25, v129
	v_mov_b32_e32 v24, v129
	v_mov_b32_e32 v23, v129
	v_mov_b32_e32 v22, v129
	v_mov_b32_e32 v21, v129
	v_mov_b32_e32 v20, v129
	v_mov_b32_e32 v19, v129
	v_mov_b32_e32 v18, v129
	v_mov_b32_e32 v9, v129
	v_mov_b32_e32 v8, v129
	v_mov_b32_e32 v7, v129
	v_mov_b32_e32 v6, v129
	v_mov_b32_e32 v5, v129
	v_mov_b32_e32 v4, v129
	v_mov_b32_e32 v3, v129
	v_mov_b32_e32 v2, v129
	s_branch .LBB0_3194

;     __device__ __forceinline__ bool next(int i, Unit& u) const { return (i < na) ? a.next(i, u) : b.next(i - na, u); }
; template <class Epi, bool ALIGN_EPI = true, bool SP2 = true, bool QUARTER = false, class Sched = Order>
; __device__ __forceinline__ void gemm_phase(PG8_LAS unsigned char* lds, const Gemm g, const Sched& S, const Epi& E) {
;     ...
;     for (;;) {
;         const bool has_next = S.next(ui + 1, nxt);
;         const char* nA = has_next ? (const char*)(g.A + (size_t)nxt.z * g.zA) + (size_t)nxt.pm * tstepA : cA; const char* nB = has_next ? (const char*)(g.Bt + (size_t)nxt.z * g.zB) + (size_t)nxt.pn * tstepB : cB;
;         for (int t = 0; t < nt; t += 2) {
;             const bool last = (t == nt - 2);
;             const char* a1 = cA + (size_t)(t + 1) * kstep;
;             const char* a2 = last ? nA : cA + (size_t)(t + 2) * kstep; const char* b2 = last ? nB : cB + (size_t)(t + 2) * kstep;
;             const char* a3 = a2 + kstep; const char* b3 = b2 + kstep;
;     ...
; #pragma unroll
;         for (int a = 0; a < 2; ++a)
; #pragma unroll
;             for (int b = 0; b < 2; ++b)
; #pragma unroll
;                 for (int m = 0; m < 4; ++m)
; #pragma unroll
;                     for (int n = 0; n < 2; ++n) acc[a][b][m][n] = (f32x4){0.f, 0.f, 0.f, 0.f};
.LBB0_3289:
	s_ashr_i32 s19, s18, 31
	s_lshl_b64 s[24:25], s[18:19], 19
	s_add_u32 s24, s10, s24
	s_addc_u32 s25, s11, s25
	s_ashr_i32 s21, s20, 31
	s_lshl_b64 s[26:27], s[20:21], 19
	s_add_u32 s26, s23, s26
	s_addc_u32 s27, s33, s27
	s_and_b64 vcc, exec, s[0:1]
	s_cbranch_vccz .Lmy_zr_11
	v_mov_b32_e32 v125, 0
	v_mov_b32_e32 v124, v125
	v_mov_b32_e32 v123, v125
	v_mov_b32_e32 v122, v125
	v_mov_b32_e32 v129, v125
	v_mov_b32_e32 v128, v125
	v_mov_b32_e32 v127, v125
	v_mov_b32_e32 v126, v125
	v_mov_b32_e32 v113, v125
	v_mov_b32_e32 v112, v125
	v_mov_b32_e32 v111, v125
	v_mov_b32_e32 v110, v125
	v_mov_b32_e32 v109, v125
	v_mov_b32_e32 v108, v125
	v_mov_b32_e32 v107, v125
	v_mov_b32_e32 v106, v125
	v_mov_b32_e32 v97, v125
	v_mov_b32_e32 v96, v125
	v_mov_b32_e32 v95, v125
	v_mov_b32_e32 v94, v125
	v_mov_b32_e32 v93, v125
	v_mov_b32_e32 v92, v125
	v_mov_b32_e32 v91, v125
	v_mov_b32_e32 v90, v125
	v_mov_b32_e32 v81, v125
	v_mov_b32_e32 v80, v125
	v_mov_b32_e32 v79, v125
	v_mov_b32_e32 v78, v125
	v_mov_b32_e32 v77, v125
	v_mov_b32_e32 v76, v125
	v_mov_b32_e32 v75, v125
	v_mov_b32_e32 v74, v125
	v_mov_b32_e32 v121, v125
	v_mov_b32_e32 v120, v125
	v_mov_b32_e32 v119, v125
	v_mov_b32_e32 v118, v125
	v_mov_b32_e32 v117, v125
	v_mov_b32_e32 v116, v125
	v_mov_b32_e32 v115, v125
	v_mov_b32_e32 v114, v125
	v_mov_b32_e32 v105, v125
	v_mov_b32_e32 v104, v125
	v_mov_b32_e32 v103, v125
	v_mov_b32_e32 v102, v125
	v_mov_b32_e32 v101, v125
	v_mov_b32_e32 v100, v125
	v_mov_b32_e32 v99, v125
	v_mov_b32_e32 v98, v125
	v_mov_b32_e32 v89, v125
	v_mov_b32_e32 v88, v125
	v_mov_b32_e32 v87, v125
	v_mov_b32_e32 v86, v125
	v_mov_b32_e32 v85, v125
	v_mov_b32_e32 v84, v125
	v_mov_b32_e32 v83, v125
	v_mov_b32_e32 v82, v125
	v_mov_b32_e32 v73, v125
	v_mov_b32_e32 v72, v125
	v_mov_b32_e32 v71, v125
	v_mov_b32_e32 v70, v125
	v_mov_b32_e32 v69, v125
	v_mov_b32_e32 v68, v125
	v_mov_b32_e32 v67, v125
	v_mov_b32_e32 v66, v125
	v_mov_b32_e32 v65, v125
	v_mov_b32_e32 v64, v125
	v_mov_b32_e32 v63, v125
	v_mov_b32_e32 v62, v125
	v_mov_b32_e32 v61, v125
	v_mov_b32_e32 v60, v125
	v_mov_b32_e32 v59, v125
	v_mov_b32_e32 v58, v125
	v_mov_b32_e32 v49, v125
	v_mov_b32_e32 v48, v125
	v_mov_b32_e32 v47, v125
	v_mov_b32_e32 v46, v125
	v_mov_b32_e32 v45, v125
	v_mov_b32_e32 v44, v125
	v_mov_b32_e32 v43, v125
	v_mov_b32_e32 v42, v125
	v_mov_b32_e32 v33, v125
	v_mov_b32_e32 v32, v125
	v_mov_b32_e32 v31, v125
	v_mov_b32_e32 v30, v125
	v_mov_b32_e32 v29, v125
	v_mov_b32_e32 v28, v125
	v_mov_b32_e32 v27, v125
	v_mov_b32_e32 v26, v125
	v_mov_b32_e32 v17, v125
	v_mov_b32_e32 v16, v125
	v_mov_b32_e32 v15, v125
	v_mov_b32_e32 v14, v125
	v_mov_b32_e32 v13, v125
	v_mov_b32_e32 v12, v125
	v_mov_b32_e32 v11, v125
	v_mov_b32_e32 v10, v125
	v_mov_b32_e32 v57, v125
	v_mov_b32_e32 v56, v125
	v_mov_b32_e32 v55, v125
	v_mov_b32_e32 v54, v125
	v_mov_b32_e32 v53, v125
	v_mov_b32_e32 v52, v125
	v_mov_b32_e32 v51, v125
	v_mov_b32_e32 v50, v125
	v_mov_b32_e32 v41, v125
	v_mov_b32_e32 v40, v125
	v_mov_b32_e32 v39, v125
	v_mov_b32_e32 v38, v125
	v_mov_b32_e32 v37, v125
	v_mov_b32_e32 v36, v125
	v_mov_b32_e32 v35, v125
	v_mov_b32_e32 v34, v125
	v_mov_b32_e32 v25, v125
	v_mov_b32_e32 v24, v125
	v_mov_b32_e32 v23, v125
	v_mov_b32_e32 v22, v125
	v_mov_b32_e32 v21, v125
	v_mov_b32_e32 v20, v125
	v_mov_b32_e32 v19, v125
	v_mov_b32_e32 v18, v125
	v_mov_b32_e32 v9, v125
	v_mov_b32_e32 v8, v125
	v_mov_b32_e32 v7, v125
	v_mov_b32_e32 v6, v125
	v_mov_b32_e32 v5, v125
	v_mov_b32_e32 v4, v125
	v_mov_b32_e32 v3, v125
	v_mov_b32_e32 v2, v125
	s_branch .LBB0_3292
.Lmy_zr_11:
	s_and_b64 s[34:35], s[2:3], exec
	s_cselect_b32 s19, s25, s31
	s_cselect_b32 s21, s24, s30
	s_cselect_b32 s22, s27, s29
	s_cselect_b32 s53, s26, s28
	s_add_u32 s54, s28, 0x100
	s_addc_u32 s55, s29, 0
	s_add_u32 s28, s30, 0x40080
	v_mov_b32_e32 v2, 0
	s_addc_u32 s29, s31, 0
	s_mov_b32 s30, 0
	v_mov_b32_e32 v3, v2
	v_mov_b32_e32 v4, v2
	v_mov_b32_e32 v5, v2
	v_mov_b32_e32 v6, v2
	v_mov_b32_e32 v7, v2
	v_mov_b32_e32 v8, v2
	v_mov_b32_e32 v9, v2
	v_mov_b32_e32 v18, v2
	v_mov_b32_e32 v19, v2
	v_mov_b32_e32 v20, v2
	v_mov_b32_e32 v21, v2
	v_mov_b32_e32 v22, v2
	v_mov_b32_e32 v23, v2
	v_mov_b32_e32 v24, v2
	v_mov_b32_e32 v25, v2
	v_mov_b32_e32 v34, v2
	v_mov_b32_e32 v35, v2
	v_mov_b32_e32 v36, v2
	v_mov_b32_e32 v37, v2
	v_mov_b32_e32 v38, v2
	v_mov_b32_e32 v39, v2
	v_mov_b32_e32 v40, v2
	v_mov_b32_e32 v41, v2
	v_mov_b32_e32 v50, v2
	v_mov_b32_e32 v51, v2
	v_mov_b32_e32 v52, v2
	v_mov_b32_e32 v53, v2
	v_mov_b32_e32 v54, v2
	v_mov_b32_e32 v55, v2
	v_mov_b32_e32 v56, v2
	v_mov_b32_e32 v57, v2
	v_mov_b32_e32 v10, v2
	v_mov_b32_e32 v11, v2
	v_mov_b32_e32 v12, v2
	v_mov_b32_e32 v13, v2
	v_mov_b32_e32 v14, v2
	v_mov_b32_e32 v15, v2
	v_mov_b32_e32 v16, v2
	v_mov_b32_e32 v17, v2
	v_mov_b32_e32 v26, v2
	v_mov_b32_e32 v27, v2
	v_mov_b32_e32 v28, v2
	v_mov_b32_e32 v29, v2
	v_mov_b32_e32 v30, v2
	v_mov_b32_e32 v31, v2
	v_mov_b32_e32 v32, v2
	v_mov_b32_e32 v33, v2
	v_mov_b32_e32 v42, v2
	v_mov_b32_e32 v43, v2
	v_mov_b32_e32 v44, v2
	v_mov_b32_e32 v45, v2
	v_mov_b32_e32 v46, v2
	v_mov_b32_e32 v47, v2
	v_mov_b32_e32 v48, v2
	v_mov_b32_e32 v49, v2
	v_mov_b32_e32 v58, v2
	v_mov_b32_e32 v59, v2
	v_mov_b32_e32 v60, v2
	v_mov_b32_e32 v61, v2
	v_mov_b32_e32 v62, v2
	v_mov_b32_e32 v63, v2
	v_mov_b32_e32 v64, v2
	v_mov_b32_e32 v65, v2
	v_mov_b32_e32 v66, v2
	v_mov_b32_e32 v67, v2
	v_mov_b32_e32 v68, v2
	v_mov_b32_e32 v69, v2
	v_mov_b32_e32 v70, v2
	v_mov_b32_e32 v71, v2
	v_mov_b32_e32 v72, v2
	v_mov_b32_e32 v73, v2
	v_mov_b32_e32 v82, v2
	v_mov_b32_e32 v83, v2
	v_mov_b32_e32 v84, v2
	v_mov_b32_e32 v85, v2
	v_mov_b32_e32 v86, v2
	v_mov_b32_e32 v87, v2
	v_mov_b32_e32 v88, v2
	v_mov_b32_e32 v89, v2
	v_mov_b32_e32 v98, v2
	v_mov_b32_e32 v99, v2
	v_mov_b32_e32 v100, v2
	v_mov_b32_e32 v101, v2
	v_mov_b32_e32 v102, v2
	v_mov_b32_e32 v103, v2
	v_mov_b32_e32 v104, v2
	v_mov_b32_e32 v105, v2
	v_mov_b32_e32 v114, v2
	v_mov_b32_e32 v115, v2
	v_mov_b32_e32 v116, v2
	v_mov_b32_e32 v117, v2
	v_mov_b32_e32 v118, v2
	v_mov_b32_e32 v119, v2
	v_mov_b32_e32 v120, v2
	v_mov_b32_e32 v121, v2
	v_mov_b32_e32 v74, v2
	v_mov_b32_e32 v75, v2
	v_mov_b32_e32 v76, v2
	v_mov_b32_e32 v77, v2
	v_mov_b32_e32 v78, v2
	v_mov_b32_e32 v79, v2
	v_mov_b32_e32 v80, v2
	v_mov_b32_e32 v81, v2
	v_mov_b32_e32 v90, v2
	v_mov_b32_e32 v91, v2
	v_mov_b32_e32 v92, v2
	v_mov_b32_e32 v93, v2
	v_mov_b32_e32 v94, v2
	v_mov_b32_e32 v95, v2
	v_mov_b32_e32 v96, v2
	v_mov_b32_e32 v97, v2
	v_mov_b32_e32 v106, v2
	v_mov_b32_e32 v107, v2
	v_mov_b32_e32 v108, v2
	v_mov_b32_e32 v109, v2
	v_mov_b32_e32 v110, v2
	v_mov_b32_e32 v111, v2
	v_mov_b32_e32 v112, v2
	v_mov_b32_e32 v113, v2
	v_mov_b32_e32 v126, v2
	v_mov_b32_e32 v127, v2
	v_mov_b32_e32 v128, v2
	v_mov_b32_e32 v129, v2
	v_mov_b32_e32 v122, v2
	v_mov_b32_e32 v123, v2
	v_mov_b32_e32 v124, v2
	v_mov_b32_e32 v125, v2
